# v43 + tiled (LDS-image) layout for the FFN activation buffer: conv epilogue and seam-fix phase store ACT as [M-tile][K-tile][half][16 KiB image]; FFN-down GEMM stages its A operand with contiguous 1 K
# speedup vs baseline: 1.0116x; 1.0030x over previous
;     __device__ __forceinline__ void operator()(const f32x4 (&acc)[2][2][4][2], const Unit& u, int wr, int wc, int fr_, int fq_) const {
;     ...
;             for (int n = 0; n < 2; ++n) {
;                 const int ch = ch0 + 4 * n;
;                 const f32x4 w0g = *(const f32x4*)(cw + ch), w1g = *(const f32x4*)(cw + NZ_ + ch), w2g = *(const f32x4*)(cw + 2 * NZ_ + ch), bg = *(const f32x4*)(cb + ch);
;                 const f32x4 w0u = *(const f32x4*)(cw + DFF_ + ch), w1u = *(const f32x4*)(cw + NZ_ + DFF_ + ch), w2u = *(const f32x4*)(cw + 2 * NZ_ + DFF_ + ch), bu = *(const f32x4*)(cb + DFF_ + ch);
;                 f32x4 pBg = zero4, pBu = zero4, nBg = zero4, nBu = zero4;
;                 if (wr == 1) { pBg = X4[XIDX(0, ai, 1) + n]; pBu = X4[XIDX(0, ai, 1) + 2 + n]; }
;                 else if (ai == 1) { pBg = X4[XIDX(1, 0, 1) + n]; pBu = X4[XIDX(1, 0, 1) + 2 + n]; }
;                 if (wr == 0) { nBg = X4[XIDX(1, ai, 0) + n]; nBu = X4[XIDX(1, ai, 0) + 2 + n]; }
;                 else if (ai == 0) { nBg = X4[XIDX(0, 1, 0) + n]; nBu = X4[XIDX(0, 1, 0) + 2 + n]; }
;                 float o[4][4];
; #pragma unroll
;                 for (int h = 0; h < 2; ++h) {
;                     typedef float f32x2 __attribute__((ext_vector_type(2)));
;     ...
;                     const f32x2 g0 = PAIR(z[ai][0][0][n]), g1 = PAIR(z[ai][0][1][n]), g2 = PAIR(z[ai][0][2][n]), g3 = PAIR(z[ai][0][3][n]);
;                     const f32x2 u0 = PAIR(z[ai][1][0][n]), u1 = PAIR(z[ai][1][1][n]), u2 = PAIR(z[ai][1][2][n]), u3 = PAIR(z[ai][1][3][n]);
;                     const f32x2 pBg2 = PAIR(pBg), nBg2 = PAIR(nBg), pBu2 = PAIR(pBu), nBu2 = PAIR(nBu);
;                     f32x2 pg, ng, pu, nu;
;                     pg.x = dpp_shr1(pBg2.x, g3.x); pg.y = dpp_shr1(pBg2.y, g3.y); ng.x = dpp_shl1(nBg2.x, g0.x); ng.y = dpp_shl1(nBg2.y, g0.y);
;                     pu.x = dpp_shr1(pBu2.x, u3.x); pu.y = dpp_shr1(pBu2.y, u3.y); nu.x = dpp_shl1(nBu2.x, u0.x); nu.y = dpp_shl1(nBu2.y, u0.y);
;                     const f32x2 A0 = PAIR(w0g), A1 = PAIR(w1g), A2 = PAIR(w2g), AB = PAIR(bg), C0 = PAIR(w0u), C1 = PAIR(w1u), C2 = PAIR(w2u), CB = PAIR(bu);
;                     f32x2 G[4], U[4];
;                     G[0] = A0 * pg + (A1 * g0 + (A2 * g1 + AB)); G[1] = A0 * g0 + (A1 * g1 + (A2 * g2 + AB)); G[2] = A0 * g1 + (A1 * g2 + (A2 * g3 + AB)); G[3] = A0 * g2 + (A1 * g3 + (A2 * ng + AB));
.LBB0_105:
	v_cvt_f32_i32_e32 v33, v33
	v_cvt_f32_i32_e32 v32, v32
	v_cvt_f32_i32_e32 v31, v31
	v_cvt_f32_i32_e32 v30, v30
	v_cvt_f32_i32_e32 v27, v27
	v_cvt_f32_i32_e32 v26, v26
	v_mov_b32_e32 v44, v238
	v_mov_b32_e32 v45, v238
	v_cvt_f32_i32_e32 v29, v29
	v_cvt_f32_i32_e32 v28, v28
	v_mov_b32_e32 v239, v238
	v_pk_mul_f32 v[56:57], v[20:21], v[44:45]
	v_pk_mul_f32 v[120:121], v[18:19], v[238:239]
	v_pk_mul_f32 v[56:57], v[56:57], v[32:33]
	v_pk_mul_f32 v[32:33], v[22:23], v[238:239]
	v_readlane_b32 s0, v255, 0
	v_pk_mul_f32 v[120:121], v[120:121], v[30:31]
	v_pk_mul_f32 v[30:31], v[24:25], v[44:45]
	v_pk_mul_f32 v[186:187], v[32:33], v[26:27]
	v_add_u32_e32 v26, s0, v94
	v_readlane_b32 s0, v255, 1
	v_pk_mul_f32 v[44:45], v[30:31], v[28:29]
	ds_read_b128 v[26:29], v26
	v_add_u32_e32 v30, s0, v94
	ds_read_b128 v[30:33], v30
	s_waitcnt vmcnt(4)
	v_pk_fma_f32 v[188:189], v[110:111], v[154:155], v[158:159]
	s_waitcnt lgkmcnt(3)
	v_mov_b32_dpp v170, v58 row_shr:1 row_mask:0xf bank_mask:0xf
	v_mov_b32_dpp v171, v59 row_shr:1 row_mask:0xf bank_mask:0xf
	v_pk_fma_f32 v[188:189], v[146:147], v[142:143], v[188:189]
	s_waitcnt lgkmcnt(1)
	v_mov_b32_dpp v26, v146 row_shl:1 row_mask:0xf bank_mask:0xf
	v_mov_b32_dpp v27, v147 row_shl:1 row_mask:0xf bank_mask:0xf
	v_pk_fma_f32 v[170:171], v[130:131], v[170:171], v[188:189]
	v_pk_fma_f32 v[188:189], v[120:121], v[154:155], v[158:159]
	s_waitcnt lgkmcnt(0)
	v_mov_b32_dpp v30, v138 row_shl:1 row_mask:0xf bank_mask:0xf
	v_mov_b32_dpp v31, v139 row_shl:1 row_mask:0xf bank_mask:0xf
	v_pk_fma_f32 v[188:189], v[110:111], v[142:143], v[188:189]
	v_pk_fma_f32 v[26:27], v[154:155], v[26:27], v[158:159]
	v_pk_fma_f32 v[146:147], v[146:147], v[130:131], v[188:189]
	v_pk_fma_f32 v[188:189], v[58:59], v[154:155], v[158:159]
	v_pk_fma_f32 v[26:27], v[58:59], v[142:143], v[26:27]
	s_waitcnt vmcnt(0)
	v_pk_fma_f32 v[30:31], v[162:163], v[30:31], v[166:167]
	s_mov_b32 s0, 0xbfb8aa3b
	v_mov_b32_dpp v102, v62 row_shr:1 row_mask:0xf bank_mask:0xf
	v_mov_b32_dpp v103, v63 row_shr:1 row_mask:0xf bank_mask:0xf
	v_pk_fma_f32 v[188:189], v[120:121], v[142:143], v[188:189]
	v_pk_fma_f32 v[26:27], v[120:121], v[130:131], v[26:27]
	v_pk_fma_f32 v[120:121], v[62:63], v[162:163], v[166:167]
	v_pk_fma_f32 v[30:31], v[62:63], v[150:151], v[30:31]
	v_pk_mul_f32 v[62:63], v[170:171], s[0:1] op_sel_hi:[1,0]
	v_pk_fma_f32 v[58:59], v[98:99], v[162:163], v[166:167]
	v_exp_f32_e32 v62, v62
	v_exp_f32_e32 v63, v63
	v_pk_fma_f32 v[58:59], v[138:139], v[150:151], v[58:59]
	v_pk_fma_f32 v[110:111], v[110:111], v[130:131], v[188:189]
	v_pk_fma_f32 v[58:59], v[134:135], v[102:103], v[58:59]
	v_pk_add_f32 v[62:63], v[62:63], 1.0 op_sel_hi:[1,0]
	v_pk_fma_f32 v[102:103], v[186:187], v[162:163], v[166:167]
	v_rcp_f32_e32 v62, v62
	v_rcp_f32_e32 v63, v63
	v_pk_fma_f32 v[102:103], v[98:99], v[150:151], v[102:103]
	v_pk_fma_f32 v[120:121], v[186:187], v[150:151], v[120:121]
	v_pk_fma_f32 v[102:103], v[138:139], v[134:135], v[102:103]
	v_pk_mul_f32 v[58:59], v[170:171], v[58:59]
	v_pk_fma_f32 v[98:99], v[98:99], v[134:135], v[120:121]
	v_pk_mul_f32 v[120:121], v[146:147], s[0:1] op_sel_hi:[1,0]
	v_pk_mul_f32 v[58:59], v[58:59], v[62:63]
	v_pk_mul_f32 v[62:63], v[146:147], v[102:103]
	v_pk_mul_f32 v[102:103], v[110:111], s[0:1] op_sel_hi:[1,0]
	v_exp_f32_e32 v120, v120
	v_exp_f32_e32 v121, v121
	v_exp_f32_e32 v102, v102
	v_exp_f32_e32 v103, v103
	v_mov_b32_dpp v28, v148 row_shl:1 row_mask:0xf bank_mask:0xf
	v_pk_add_f32 v[120:121], v[120:121], 1.0 op_sel_hi:[1,0]
	v_mov_b32_dpp v29, v149 row_shl:1 row_mask:0xf bank_mask:0xf
	v_pk_add_f32 v[102:103], v[102:103], 1.0 op_sel_hi:[1,0]
	v_rcp_f32_e32 v120, v120
	v_rcp_f32_e32 v121, v121
	v_rcp_f32_e32 v102, v102
	v_rcp_f32_e32 v103, v103
	v_pk_fma_f32 v[28:29], v[156:157], v[28:29], v[160:161]
	v_pk_fma_f32 v[30:31], v[186:187], v[134:135], v[30:31]
	v_pk_mul_f32 v[98:99], v[110:111], v[98:99]
	v_pk_fma_f32 v[110:111], v[60:61], v[156:157], v[160:161]
	v_pk_fma_f32 v[28:29], v[60:61], v[144:145], v[28:29]
	v_pk_mul_f32 v[62:63], v[62:63], v[120:121]
	v_pk_mul_f32 v[120:121], v[26:27], s[0:1] op_sel_hi:[1,0]
	v_pk_mul_f32 v[102:103], v[98:99], v[102:103]
	v_pk_mul_f32 v[26:27], v[26:27], v[30:31]
	v_mov_b32_dpp v32, v140 row_shl:1 row_mask:0xf bank_mask:0xf
	v_mov_b32_dpp v33, v141 row_shl:1 row_mask:0xf bank_mask:0xf
	v_pk_fma_f32 v[30:31], v[112:113], v[156:157], v[160:161]
	v_pk_fma_f32 v[98:99], v[56:57], v[156:157], v[160:161]
	v_pk_fma_f32 v[110:111], v[56:57], v[144:145], v[110:111]
	v_pk_fma_f32 v[28:29], v[56:57], v[132:133], v[28:29]
	v_pk_fma_f32 v[56:57], v[100:101], v[164:165], v[168:169]
	v_mov_b32_dpp v172, v60 row_shr:1 row_mask:0xf bank_mask:0xf
	v_mov_b32_dpp v173, v61 row_shr:1 row_mask:0xf bank_mask:0xf
	v_mov_b32_dpp v104, v64 row_shr:1 row_mask:0xf bank_mask:0xf
	v_mov_b32_dpp v105, v65 row_shr:1 row_mask:0xf bank_mask:0xf
	v_pk_fma_f32 v[30:31], v[148:149], v[144:145], v[30:31]
;     __device__ __forceinline__ void operator()(const f32x4 (&acc)[2][2][4][2], const Unit& u, int wr, int wc, int fr_, int fq_) const {
;     ...
;                 const f32x4 w0g = *(const f32x4*)(cw + ch), w1g = *(const f32x4*)(cw + NZ_ + ch), w2g = *(const f32x4*)(cw + 2 * NZ_ + ch), bg = *(const f32x4*)(cb + ch);
;                 const f32x4 w0u = *(const f32x4*)(cw + DFF_ + ch), w1u = *(const f32x4*)(cw + NZ_ + DFF_ + ch), w2u = *(const f32x4*)(cw + 2 * NZ_ + DFF_ + ch), bu = *(const f32x4*)(cb + DFF_ + ch);
;                 f32x4 pBg = zero4, pBu = zero4, nBg = zero4, nBu = zero4;
;                 if (wr == 1) { pBg = X4[XIDX(0, ai, 1) + n]; pBu = X4[XIDX(0, ai, 1) + 2 + n]; }
;                 else if (ai == 1) { pBg = X4[XIDX(1, 0, 1) + n]; pBu = X4[XIDX(1, 0, 1) + 2 + n]; }
;                 if (wr == 0) { nBg = X4[XIDX(1, ai, 0) + n]; nBu = X4[XIDX(1, ai, 0) + 2 + n]; }
;                 else if (ai == 0) { nBg = X4[XIDX(0, 1, 0) + n]; nBu = X4[XIDX(0, 1, 0) + 2 + n]; }
;     ...
;                     G[0] = A0 * pg + (A1 * g0 + (A2 * g1 + AB)); G[1] = A0 * g0 + (A1 * g1 + (A2 * g2 + AB)); G[2] = A0 * g1 + (A1 * g2 + (A2 * g3 + AB)); G[3] = A0 * g2 + (A1 * g3 + (A2 * ng + AB));
;                     U[0] = C0 * pu + (C1 * u0 + (C2 * u1 + CB)); U[1] = C0 * u0 + (C1 * u1 + (C2 * u2 + CB)); U[2] = C0 * u1 + (C1 * u2 + (C2 * u3 + CB)); U[3] = C0 * u2 + (C1 * u3 + (C2 * nu + CB));
; #pragma unroll
;                     for (int m = 0; m < 4; ++m) {
;                         const f32x2 t = G[m] * (-1.4426950408889634f);
;                         f32x2 e; e.x = __builtin_amdgcn_exp2f(t.x); e.y = __builtin_amdgcn_exp2f(t.y);
;                         const f32x2 d = e + 1.0f;
;                         f32x2 r; r.x = __builtin_amdgcn_rcpf(d.x); r.y = __builtin_amdgcn_rcpf(d.y);
;                         const f32x2 q = (G[m] * U[m]) * r;
;                         o[m][2 * h] = q.x; o[m][2 * h + 1] = q.y;
;                     }
;     ...
;                 }
; #pragma unroll
;                 for (int m = 0; m < 4; ++m) { ow[m][2 * n] = cvt_pk_bf16(o[m][0], o[m][1]); ow[m][2 * n + 1] = cvt_pk_bf16(o[m][2], o[m][3]); }
;             }
; #pragma unroll
;             for (int m = 0; m < 4; ++m) { u32x4 w; w.x = ow[m][0]; w.y = ow[m][1]; w.z = ow[m][2]; w.w = ow[m][3];
;                 *(u32x4*)(ACT + (size_t)(rowb + ai * HALF + m) * DFF_ + ch0) = w; }
	v_pk_fma_f32 v[56:57], v[140:141], v[152:153], v[56:57]
	v_pk_fma_f32 v[32:33], v[164:165], v[32:33], v[168:169]
	v_pk_fma_f32 v[30:31], v[132:133], v[172:173], v[30:31]
	v_pk_fma_f32 v[56:57], v[136:137], v[104:105], v[56:57]
	v_pk_fma_f32 v[104:105], v[64:65], v[164:165], v[168:169]
	v_pk_fma_f32 v[32:33], v[64:65], v[152:153], v[32:33]
	v_pk_fma_f32 v[60:61], v[44:45], v[164:165], v[168:169]
	v_pk_fma_f32 v[104:105], v[44:45], v[152:153], v[104:105]
	v_pk_fma_f32 v[32:33], v[44:45], v[136:137], v[32:33]
	v_pk_mul_f32 v[44:45], v[30:31], s[0:1] op_sel_hi:[1,0]
	v_pk_fma_f32 v[98:99], v[112:113], v[144:145], v[98:99]
	v_exp_f32_e32 v44, v44
	v_exp_f32_e32 v45, v45
	v_pk_fma_f32 v[98:99], v[148:149], v[132:133], v[98:99]
	v_pk_fma_f32 v[60:61], v[100:101], v[152:153], v[60:61]
	v_pk_fma_f32 v[110:111], v[112:113], v[132:133], v[110:111]
	v_pk_add_f32 v[44:45], v[44:45], 1.0 op_sel_hi:[1,0]
	v_pk_fma_f32 v[60:61], v[140:141], v[136:137], v[60:61]
	v_rcp_f32_e32 v44, v44
	v_rcp_f32_e32 v45, v45
	v_pk_mul_f32 v[64:65], v[98:99], s[0:1] op_sel_hi:[1,0]
	v_pk_mul_f32 v[30:31], v[30:31], v[56:57]
	v_exp_f32_e32 v120, v120
	v_exp_f32_e32 v121, v121
	v_exp_f32_e32 v64, v64
	v_exp_f32_e32 v65, v65
	v_pk_mul_f32 v[30:31], v[30:31], v[44:45]
	v_pk_mul_f32 v[44:45], v[98:99], v[60:61]
	v_pk_mul_f32 v[56:57], v[110:111], s[0:1] op_sel_hi:[1,0]
	v_pk_mul_f32 v[60:61], v[28:29], s[0:1] op_sel_hi:[1,0]
	v_exp_f32_e32 v56, v56
	v_exp_f32_e32 v57, v57
	v_exp_f32_e32 v60, v60
	v_exp_f32_e32 v61, v61
	v_pk_add_f32 v[120:121], v[120:121], 1.0 op_sel_hi:[1,0]
	v_pk_add_f32 v[64:65], v[64:65], 1.0 op_sel_hi:[1,0]
	v_rcp_f32_e32 v120, v120
	v_rcp_f32_e32 v121, v121
	v_rcp_f32_e32 v64, v64
	v_rcp_f32_e32 v65, v65
	v_pk_add_f32 v[56:57], v[56:57], 1.0 op_sel_hi:[1,0]
	v_pk_add_f32 v[60:61], v[60:61], 1.0 op_sel_hi:[1,0]
	v_rcp_f32_e32 v56, v56
	v_rcp_f32_e32 v57, v57
	v_rcp_f32_e32 v60, v60
	v_rcp_f32_e32 v61, v61
	v_pk_fma_f32 v[100:101], v[100:101], v[136:137], v[104:105]
	v_readlane_b32 s0, v252, 18
	v_readlane_b32 s100, v252, 18
	v_readlane_b32 s101, v252, 19
	v_pk_mul_f32 v[26:27], v[26:27], v[120:121]
	v_pk_mul_f32 v[44:45], v[44:45], v[64:65]
	v_pk_mul_f32 v[64:65], v[110:111], v[100:101]
	v_pk_mul_f32 v[28:29], v[28:29], v[32:33]
	v_readlane_b32 s1, v252, 19
	v_pk_mul_f32 v[64:65], v[64:65], v[56:57]
	v_pk_mul_f32 v[28:29], v[28:29], v[60:61]
	v_cvt_pk_bf16_f32 v120, v58, v59
	v_cvt_pk_bf16_f32 v121, v30, v31
	v_cvt_pk_bf16_f32 v98, v62, v63
	v_cvt_pk_bf16_f32 v99, v44, v45
	v_cvt_pk_bf16_f32 v56, v102, v103
	v_cvt_pk_bf16_f32 v57, v64, v65
	v_cvt_pk_bf16_f32 v44, v26, v27
	v_mov_b64_e32 v[26:27], s[0:1]
	s_movk_i32 s4, 0x2c00
	v_cvt_pk_bf16_f32 v45, v28, v29
	v_lshrrev_b32_e32 v208, 8, v220
	v_mul_u32_u24_e32 v208, 0x2c0000, v208
	v_lshrrev_b32_e32 v209, 6, v236
	v_lshl_add_u32 v208, v209, 15, v208
	v_bfe_u32 v209, v220, 4, 4
	v_lshl_add_u32 v208, v209, 11, v208
	v_bfe_u32 v209, v236, 5, 1
	v_lshl_add_u32 v208, v209, 10, v208
	v_and_b32_e32 v209, 15, v220
	v_lshlrev_b32_e32 v209, 6, v209
	v_lshlrev_b32_e32 v26, 1, v236
	v_and_or_b32 v209, v26, 48, v209
	v_bfe_u32 v26, v220, 3, 1
	v_lshlrev_b32_e32 v26, 5, v26
	v_xor_b32_e32 v209, v209, v26
	v_add_u32_e32 v208, v208, v209
	v_add_u32_e32 v209, 0x4000, v208
	v_lshlrev_b64 v[142:143], 1, v[236:237]
	v_or_b32_e32 v190, 1, v220
	global_store_dwordx4 v208, v[118:121], s[100:101]
	v_or_b32_e32 v191, 2, v220
	v_or_b32_e32 v192, 3, v220
	global_store_dwordx4 v208, v[96:99], s[100:101] offset:64
	global_store_dwordx4 v208, v[54:57], s[100:101] offset:128
	global_store_dwordx4 v208, v[42:45], s[100:101] offset:192
	global_load_dwordx4 v[62:65], v[78:79], off
	global_load_dwordx4 v[96:99], v[224:225], off
	global_load_dwordx4 v[100:103], v[226:227], off
	global_load_dwordx4 v[110:113], v[222:223], off
	global_load_dwordx4 v[28:31], v[228:229], off
	global_load_dwordx4 v[42:45], v[230:231], off
	global_load_dwordx4 v[54:57], v[232:233], off
	global_load_dwordx4 v[58:61], v[234:235], off
	v_readlane_b32 s0, v255, 12
	v_add_u32_e32 v26, 0x1100, v94
	v_add_u32_e32 v104, 0x1120, v94
	v_add_u32_e32 v33, s0, v205
	v_add_u32_e32 v27, 0x100, v33
	v_add_u32_e32 v32, 0x120, v33
	v_cndmask_b32_e64 v26, v26, v27, s[46:47]
	v_cndmask_b32_e64 v32, v104, v32, s[46:47]
	ds_read_b128 v[134:137], v26
	ds_read_b128 v[118:121], v32
	v_readlane_b32 s4, v254, 44
	v_readlane_b32 s5, v254, 45
	v_mov_b32_e32 v26, 0
	s_andn2_b64 vcc, exec, s[4:5]
	v_cndmask_b32_e64 v27, 0, 1, s[4:5]
	v_cmp_ne_u32_e64 s[0:1], 1, v27
	v_mov_b32_e32 v138, 0
	v_mov_b32_e32 v139, 0
	v_mov_b32_e32 v140, 0
	v_mov_b32_e32 v141, 0
	v_mov_b32_e32 v130, 0
	v_mov_b32_e32 v131, 0
	v_mov_b32_e32 v132, 0
	v_mov_b32_e32 v133, 0
	v_mov_b32_e32 v244, v206
	v_mov_b32_e32 v246, v202
	v_mov_b32_e32 v202, v207
	v_mov_b32_e32 v245, v221
	s_cbranch_vccnz .LBB0_107
	ds_read_b128 v[138:141], v33 offset:4096
	ds_read_b128 v[130:133], v33 offset:4128

;     __device__ __forceinline__ void operator()(const f32x4 (&acc)[2][2][4][2], const Unit& u, int wr, int wc, int fr_, int fq_) const {
;     ...
;             for (int m = 0; m < 4; ++m) { const float r = rstd2048(rs, rowb + ai * HALF + m) * sx[rowb + ai * HALF + m];
; #pragma unroll
;                 for (int bj = 0; bj < 2; ++bj)
; #pragma unroll
;                     for (int n = 0; n < 2; ++n) { typedef int i32x4 __attribute__((ext_vector_type(4)));
;     ...
;                     const f32x2 g0 = PAIR(z[ai][0][0][n]), g1 = PAIR(z[ai][0][1][n]), g2 = PAIR(z[ai][0][2][n]), g3 = PAIR(z[ai][0][3][n]);
;                     const f32x2 u0 = PAIR(z[ai][1][0][n]), u1 = PAIR(z[ai][1][1][n]), u2 = PAIR(z[ai][1][2][n]), u3 = PAIR(z[ai][1][3][n]);
;                     const f32x2 pBg2 = PAIR(pBg), nBg2 = PAIR(nBg), pBu2 = PAIR(pBu), nBu2 = PAIR(nBu);
;                     f32x2 pg, ng, pu, nu;
;                     pg.x = dpp_shr1(pBg2.x, g3.x); pg.y = dpp_shr1(pBg2.y, g3.y); ng.x = dpp_shl1(nBg2.x, g0.x); ng.y = dpp_shl1(nBg2.y, g0.y);
;                     pu.x = dpp_shr1(pBu2.x, u3.x); pu.y = dpp_shr1(pBu2.y, u3.y); nu.x = dpp_shl1(nBu2.x, u0.x); nu.y = dpp_shl1(nBu2.y, u0.y);
;                     const f32x2 A0 = PAIR(w0g), A1 = PAIR(w1g), A2 = PAIR(w2g), AB = PAIR(bg), C0 = PAIR(w0u), C1 = PAIR(w1u), C2 = PAIR(w2u), CB = PAIR(bu);
;                     f32x2 G[4], U[4];
;                     G[0] = A0 * pg + (A1 * g0 + (A2 * g1 + AB)); G[1] = A0 * g0 + (A1 * g1 + (A2 * g2 + AB)); G[2] = A0 * g1 + (A1 * g2 + (A2 * g3 + AB)); G[3] = A0 * g2 + (A1 * g3 + (A2 * ng + AB));
;                     U[0] = C0 * pu + (C1 * u0 + (C2 * u1 + CB)); U[1] = C0 * u0 + (C1 * u1 + (C2 * u2 + CB)); U[2] = C0 * u1 + (C1 * u2 + (C2 * u3 + CB)); U[3] = C0 * u2 + (C1 * u3 + (C2 * nu + CB));
; #pragma unroll
;                     for (int m = 0; m < 4; ++m) {
;                         const f32x2 t = G[m] * (-1.4426950408889634f);
;                         f32x2 e; e.x = __builtin_amdgcn_exp2f(t.x); e.y = __builtin_amdgcn_exp2f(t.y);
;                         const f32x2 d = e + 1.0f;
;                         f32x2 r; r.x = __builtin_amdgcn_rcpf(d.x); r.y = __builtin_amdgcn_rcpf(d.y);
;                         const f32x2 q = (G[m] * U[m]) * r;
;                         o[m][2 * h] = q.x; o[m][2 * h + 1] = q.y;
;                     }
.LBB0_109:
	v_cvt_f32_i32_e32 v9, v9
	v_cvt_f32_i32_e32 v8, v8
	v_mov_b32_e32 v12, v32
	v_mov_b32_e32 v13, v32
	v_cvt_f32_i32_e32 v5, v5
	v_cvt_f32_i32_e32 v4, v4
	s_waitcnt lgkmcnt(1)
	v_mov_b32_dpp v26, v46 row_shl:1 row_mask:0xf bank_mask:0xf
	v_mov_b32_dpp v27, v47 row_shl:1 row_mask:0xf bank_mask:0xf
	v_pk_mul_f32 v[16:17], v[24:25], v[12:13]
	v_cvt_f32_i32_e32 v7, v7
	v_cvt_f32_i32_e32 v6, v6
	v_pk_mul_f32 v[12:13], v[20:21], v[12:13]
	v_mov_b32_e32 v33, v32
	v_pk_mul_f32 v[8:9], v[12:13], v[8:9]
	s_waitcnt vmcnt(4)
	v_pk_fma_f32 v[12:13], v[82:83], v[26:27], v[90:91]
	v_pk_mul_f32 v[4:5], v[16:17], v[4:5]
	v_pk_fma_f32 v[12:13], v[66:67], v[78:79], v[12:13]
	v_pk_mul_f32 v[16:17], v[18:19], v[32:33]
	v_pk_fma_f32 v[12:13], v[86:87], v[62:63], v[12:13]
	s_mov_b32 s0, 0xbfb8aa3b
	v_cvt_f32_i32_e32 v3, v3
	v_cvt_f32_i32_e32 v2, v2
	v_pk_mul_f32 v[6:7], v[16:17], v[6:7]
	v_pk_mul_f32 v[16:17], v[12:13], s[0:1] op_sel_hi:[1,0]
	v_pk_fma_f32 v[20:21], v[66:67], v[82:83], v[90:91]
	v_exp_f32_e32 v16, v16
	v_exp_f32_e32 v17, v17
	v_pk_fma_f32 v[20:21], v[86:87], v[78:79], v[20:21]
	v_pk_mul_f32 v[22:23], v[22:23], v[32:33]
	v_pk_fma_f32 v[20:21], v[6:7], v[62:63], v[20:21]
	v_pk_mul_f32 v[2:3], v[22:23], v[2:3]
	v_pk_mul_f32 v[22:23], v[20:21], s[0:1] op_sel_hi:[1,0]
	s_waitcnt lgkmcnt(0)
	v_mov_b32_dpp v98, v50 row_shl:1 row_mask:0xf bank_mask:0xf
	v_mov_b32_dpp v99, v51 row_shl:1 row_mask:0xf bank_mask:0xf
	v_pk_add_f32 v[16:17], v[16:17], 1.0 op_sel_hi:[1,0]
	v_exp_f32_e32 v22, v22
	v_exp_f32_e32 v23, v23
	s_waitcnt vmcnt(0)
; __device__ __forceinline__ unsigned cvt_pk_bf16(float lo, float hi) { unsigned r; asm volatile("v_cvt_pk_bf16_f32 %0, %1, %2" : "=v"(r) : "v"(lo), "v"(hi)); return r; }
;     __device__ __forceinline__ void operator()(const f32x4 (&acc)[2][2][4][2], const Unit& u, int wr, int wc, int fr_, int fq_) const {
;     ...
;                     G[0] = A0 * pg + (A1 * g0 + (A2 * g1 + AB)); G[1] = A0 * g0 + (A1 * g1 + (A2 * g2 + AB)); G[2] = A0 * g1 + (A1 * g2 + (A2 * g3 + AB)); G[3] = A0 * g2 + (A1 * g3 + (A2 * ng + AB));
;                     U[0] = C0 * pu + (C1 * u0 + (C2 * u1 + CB)); U[1] = C0 * u0 + (C1 * u1 + (C2 * u2 + CB)); U[2] = C0 * u1 + (C1 * u2 + (C2 * u3 + CB)); U[3] = C0 * u2 + (C1 * u3 + (C2 * nu + CB));
; #pragma unroll
;                     for (int m = 0; m < 4; ++m) {
;                         const f32x2 t = G[m] * (-1.4426950408889634f);
;                         f32x2 e; e.x = __builtin_amdgcn_exp2f(t.x); e.y = __builtin_amdgcn_exp2f(t.y);
;                         const f32x2 d = e + 1.0f;
;                         f32x2 r; r.x = __builtin_amdgcn_rcpf(d.x); r.y = __builtin_amdgcn_rcpf(d.y);
;                         const f32x2 q = (G[m] * U[m]) * r;
;                         o[m][2 * h] = q.x; o[m][2 * h + 1] = q.y;
;                     }
;     ...
;                 }
; #pragma unroll
;                 for (int m = 0; m < 4; ++m) { ow[m][2 * n] = cvt_pk_bf16(o[m][0], o[m][1]); ow[m][2 * n + 1] = cvt_pk_bf16(o[m][2], o[m][3]); }
;             }
; #pragma unroll
;             for (int m = 0; m < 4; ++m) { u32x4 w; w.x = ow[m][0]; w.y = ow[m][1]; w.z = ow[m][2]; w.w = ow[m][3];
;                 *(u32x4*)(ACT + (size_t)(rowb + ai * HALF + m) * DFF_ + ch0) = w; }
	v_pk_fma_f32 v[18:19], v[54:55], v[98:99], v[58:59]
	v_rcp_f32_e32 v16, v16
	v_rcp_f32_e32 v17, v17
	v_pk_fma_f32 v[18:19], v[70:71], v[40:41], v[18:19]
	v_mov_b32_dpp v102, v66 row_shr:1 row_mask:0xf bank_mask:0xf
	v_pk_fma_f32 v[18:19], v[74:75], v[36:37], v[18:19]
	v_mov_b32_dpp v103, v67 row_shr:1 row_mask:0xf bank_mask:0xf
	v_pk_mul_f32 v[12:13], v[12:13], v[18:19]
	v_pk_add_f32 v[18:19], v[22:23], 1.0 op_sel_hi:[1,0]
	v_pk_mul_f32 v[12:13], v[12:13], v[16:17]
	v_pk_fma_f32 v[16:17], v[70:71], v[54:55], v[58:59]
	v_rcp_f32_e32 v18, v18
	v_rcp_f32_e32 v19, v19
	v_pk_fma_f32 v[16:17], v[74:75], v[40:41], v[16:17]
	v_pk_fma_f32 v[22:23], v[74:75], v[54:55], v[58:59]
	v_pk_fma_f32 v[16:17], v[2:3], v[36:37], v[16:17]
	v_pk_fma_f32 v[22:23], v[2:3], v[40:41], v[22:23]
	v_pk_mul_f32 v[16:17], v[20:21], v[16:17]
	v_pk_fma_f32 v[22:23], v[50:51], v[36:37], v[22:23]
	v_pk_mul_f32 v[16:17], v[16:17], v[18:19]
	v_pk_fma_f32 v[18:19], v[86:87], v[82:83], v[90:91]
	v_pk_fma_f32 v[2:3], v[2:3], v[54:55], v[58:59]
	v_pk_fma_f32 v[18:19], v[6:7], v[78:79], v[18:19]
	v_pk_fma_f32 v[6:7], v[6:7], v[82:83], v[90:91]
	v_pk_fma_f32 v[18:19], v[46:47], v[62:63], v[18:19]
	v_pk_fma_f32 v[6:7], v[46:47], v[78:79], v[6:7]
	v_pk_mul_f32 v[20:21], v[18:19], s[0:1] op_sel_hi:[1,0]
	v_pk_fma_f32 v[6:7], v[62:63], v[102:103], v[6:7]
	v_exp_f32_e32 v20, v20
	v_exp_f32_e32 v21, v21
	v_pk_mul_f32 v[24:25], v[6:7], s[0:1] op_sel_hi:[1,0]
	v_pk_mul_f32 v[18:19], v[18:19], v[22:23]
	v_exp_f32_e32 v24, v24
	v_pk_add_f32 v[20:21], v[20:21], 1.0 op_sel_hi:[1,0]
	v_exp_f32_e32 v25, v25
	v_rcp_f32_e32 v20, v20
	v_rcp_f32_e32 v21, v21
	v_mov_b32_dpp v94, v70 row_shr:1 row_mask:0xf bank_mask:0xf
	v_mov_b32_dpp v95, v71 row_shr:1 row_mask:0xf bank_mask:0xf
	v_pk_fma_f32 v[2:3], v[50:51], v[40:41], v[2:3]
	v_pk_mul_f32 v[18:19], v[18:19], v[20:21]
	v_pk_add_f32 v[20:21], v[24:25], 1.0 op_sel_hi:[1,0]
	v_pk_fma_f32 v[2:3], v[36:37], v[94:95], v[2:3]
	v_rcp_f32_e32 v20, v20
	v_rcp_f32_e32 v21, v21
	v_pk_mul_f32 v[2:3], v[6:7], v[2:3]
	v_pk_fma_f32 v[6:7], v[8:9], v[84:85], v[92:93]
	v_pk_fma_f32 v[22:23], v[68:69], v[84:85], v[92:93]
	v_pk_mul_f32 v[2:3], v[2:3], v[20:21]
	v_pk_fma_f32 v[20:21], v[88:89], v[84:85], v[92:93]
	v_pk_fma_f32 v[24:25], v[4:5], v[56:57], v[60:61]
	v_mov_b32_dpp v104, v68 row_shr:1 row_mask:0xf bank_mask:0xf
	v_mov_b32_dpp v105, v69 row_shr:1 row_mask:0xf bank_mask:0xf
	v_mov_b32_dpp v96, v72 row_shr:1 row_mask:0xf bank_mask:0xf
	v_mov_b32_dpp v97, v73 row_shr:1 row_mask:0xf bank_mask:0xf
	v_pk_fma_f32 v[6:7], v[48:49], v[80:81], v[6:7]
	v_pk_fma_f32 v[20:21], v[8:9], v[80:81], v[20:21]
	v_pk_fma_f32 v[22:23], v[88:89], v[80:81], v[22:23]
	v_pk_fma_f32 v[24:25], v[52:53], v[42:43], v[24:25]
	v_mov_b32_dpp v28, v48 row_shl:1 row_mask:0xf bank_mask:0xf
	v_mov_b32_dpp v29, v49 row_shl:1 row_mask:0xf bank_mask:0xf
	v_pk_fma_f32 v[6:7], v[64:65], v[104:105], v[6:7]
	v_pk_fma_f32 v[20:21], v[48:49], v[64:65], v[20:21]
	v_pk_fma_f32 v[8:9], v[8:9], v[64:65], v[22:23]
	v_pk_fma_f32 v[24:25], v[38:39], v[96:97], v[24:25]
	v_pk_fma_f32 v[22:23], v[84:85], v[28:29], v[92:93]
	v_pk_fma_f32 v[26:27], v[76:77], v[56:57], v[60:61]
	v_pk_mul_f32 v[32:33], v[6:7], s[0:1] op_sel_hi:[1,0]
	v_pk_mul_f32 v[36:37], v[20:21], s[0:1] op_sel_hi:[1,0]
	v_pk_mul_f32 v[6:7], v[6:7], v[24:25]
	v_pk_mul_f32 v[24:25], v[8:9], s[0:1] op_sel_hi:[1,0]
	v_pk_fma_f32 v[22:23], v[68:69], v[80:81], v[22:23]
	v_pk_fma_f32 v[26:27], v[4:5], v[42:43], v[26:27]
	v_exp_f32_e32 v36, v36
	v_exp_f32_e32 v37, v37
	v_exp_f32_e32 v24, v24
	v_exp_f32_e32 v25, v25
	v_pk_fma_f32 v[22:23], v[88:89], v[64:65], v[22:23]
	v_pk_fma_f32 v[26:27], v[52:53], v[38:39], v[26:27]
	v_exp_f32_e32 v32, v32
	v_exp_f32_e32 v33, v33
	v_pk_mul_f32 v[20:21], v[20:21], v[26:27]
	v_pk_mul_f32 v[26:27], v[22:23], s[0:1] op_sel_hi:[1,0]
	v_pk_add_f32 v[36:37], v[36:37], 1.0 op_sel_hi:[1,0]
	v_exp_f32_e32 v26, v26
	v_exp_f32_e32 v27, v27
	v_pk_add_f32 v[24:25], v[24:25], 1.0 op_sel_hi:[1,0]
	v_pk_fma_f32 v[28:29], v[72:73], v[56:57], v[60:61]
	v_pk_add_f32 v[32:33], v[32:33], 1.0 op_sel_hi:[1,0]
	v_rcp_f32_e32 v36, v36
	v_rcp_f32_e32 v37, v37
	v_rcp_f32_e32 v24, v24
	v_rcp_f32_e32 v25, v25
	v_pk_fma_f32 v[28:29], v[76:77], v[42:43], v[28:29]
	v_rcp_f32_e32 v32, v32
	v_rcp_f32_e32 v33, v33
	v_mov_b32_dpp v100, v52 row_shl:1 row_mask:0xf bank_mask:0xf
	v_mov_b32_dpp v101, v53 row_shl:1 row_mask:0xf bank_mask:0xf
	v_pk_fma_f32 v[4:5], v[4:5], v[38:39], v[28:29]
	v_pk_add_f32 v[26:27], v[26:27], 1.0 op_sel_hi:[1,0]
	v_readlane_b32 s0, v252, 18
	v_pk_fma_f32 v[28:29], v[56:57], v[100:101], v[60:61]
	v_rcp_f32_e32 v26, v26
	v_rcp_f32_e32 v27, v27
	v_pk_mul_f32 v[4:5], v[8:9], v[4:5]
	v_readlane_b32 s1, v252, 19
	v_add_u32_e32 v44, 0x80, v220
	v_pk_fma_f32 v[28:29], v[72:73], v[42:43], v[28:29]
	v_pk_mul_f32 v[20:21], v[20:21], v[36:37]
	v_pk_mul_f32 v[4:5], v[4:5], v[24:25]
	v_cvt_pk_bf16_f32 v36, v2, v3
	v_mov_b64_e32 v[2:3], s[0:1]
	s_movk_i32 s4, 0x2c00
	v_pk_fma_f32 v[28:29], v[76:77], v[38:39], v[28:29]
	v_pk_mul_f32 v[6:7], v[6:7], v[32:33]
	v_add_u32_e32 v45, 0x81, v220
	v_cvt_pk_bf16_f32 v37, v6, v7
	v_cvt_pk_bf16_f32 v32, v18, v19
	v_cvt_pk_bf16_f32 v33, v20, v21
	v_cvt_pk_bf16_f32 v16, v16, v17
	v_cvt_pk_bf16_f32 v17, v4, v5
	v_mad_i64_i32 v[4:5], s[0:1], v44, s4, v[2:3]
	v_pk_mul_f32 v[8:9], v[22:23], v[28:29]
	v_pk_mul_f32 v[8:9], v[8:9], v[26:27]
	v_cvt_pk_bf16_f32 v12, v12, v13
	v_add_u32_e32 v106, 0x82, v220
	v_cvt_pk_bf16_f32 v13, v8, v9
	global_store_dwordx4 v209, v[34:37], s[100:101]
	v_add_u32_e32 v107, 0x83, v220
	global_store_dwordx4 v209, v[30:33], s[100:101] offset:64
	global_store_dwordx4 v209, v[14:17], s[100:101] offset:128
	global_store_dwordx4 v209, v[10:13], s[100:101] offset:192
	v_readlane_b32 s0, v254, 42
	v_readlane_b32 s1, v254, 43
	s_andn2_b64 vcc, exec, s[0:1]
	s_mov_b64 s[0:1], -1
	s_cbranch_vccnz .LBB0_76
	s_and_b64 vcc, exec, s[8:9]
	s_cbranch_vccnz .LBB0_75
	s_barrier
	s_branch .LBB0_75

; __device__ __forceinline__ unsigned cvt_pk_bf16(float lo, float hi) { unsigned r; asm volatile("v_cvt_pk_bf16_f32 %0, %1, %2" : "=v"(r) : "v"(lo), "v"(hi)); return r; }
; __device__ __forceinline__ float silu_f(float g) { return g * __builtin_amdgcn_rcpf(1.0f + __builtin_amdgcn_exp2f(-1.4426950408889634f * g)); }
; __device__ __forceinline__ void ffn_fix_phase(const float* HZ, const float* cw, const float* cb, bf16* ACT, int tid) {
;     ...
;         const int ri = it / NC4, c4 = it - ri * NC4, pm = ri >> 1, last = ri & 1, t = pm * 256 + last * 255, ch = 4 * c4;
;         const int gi = (ch >> 7) * 256 + (ch & 127), ui = gi + 128;
;         const float* hp = last ? HZ + (size_t)(pm * 4 + 2) * NZ : (seq_start(t) ? nullptr : HZ + (size_t)(pm * 4 - 1) * NZ);
;         const float* hc = HZ + (size_t)(pm * 4 + (last ? 3 : 0)) * NZ;
;         const float* hn = last ? (seq_start(t + 1) ? nullptr : HZ + (size_t)(pm * 4 + 4) * NZ) : HZ + (size_t)(pm * 4 + 1) * NZ;
;         const f32x4 pg = hp ? *(const f32x4*)(hp + gi) : zero4, pu = hp ? *(const f32x4*)(hp + ui) : zero4;
;         const f32x4 cg_ = *(const f32x4*)(hc + gi), cu = *(const f32x4*)(hc + ui);
;         const f32x4 ng = hn ? *(const f32x4*)(hn + gi) : zero4, nu = hn ? *(const f32x4*)(hn + ui) : zero4;
;         const f32x4 w0g = *(const f32x4*)(cw + ch), w1g = *(const f32x4*)(cw + NZ + ch), w2g = *(const f32x4*)(cw + 2 * NZ + ch), bg = *(const f32x4*)(cb + ch);
;         const f32x4 w0u = *(const f32x4*)(cw + DFF + ch), w1u = *(const f32x4*)(cw + NZ + DFF + ch), w2u = *(const f32x4*)(cw + 2 * NZ + DFF + ch), bu = *(const f32x4*)(cb + DFF + ch);
;         float o[4];
; #pragma unroll
;         for (int j = 0; j < 4; ++j) {
;             const float g = w0g[j] * pg[j] + w1g[j] * cg_[j] + w2g[j] * ng[j] + bg[j];
;             const float u = w0u[j] * pu[j] + w1u[j] * cu[j] + w2u[j] * nu[j] + bu[j];
;             o[j] = pg8::silu_f(g) * u;
;         }
;         u32x2v w; w.x = cvt_pk_bf16(o[0], o[1]); w.y = cvt_pk_bf16(o[2], o[3]);
;         *(u32x2v*)(ACT + (size_t)t * DFF + ch) = w;
.LBB0_121:
	s_or_b64 exec, exec, s[0:1]
	v_ashrrev_i32_e32 v47, 31, v46
	v_lshlrev_b64 v[38:39], 2, v[46:47]
	v_lshl_add_u64 v[34:35], s[44:45], 0, v[38:39]
	v_lshl_add_u64 v[18:19], s[8:9], 0, v[38:39]
	v_lshl_add_u64 v[22:23], s[40:41], 0, v[38:39]
	global_load_dwordx4 v[58:61], v[34:35], off
	v_lshl_add_u64 v[34:35], s[70:71], 0, v[38:39]
	global_load_dwordx4 v[18:21], v[18:19], off
	v_lshl_add_u64 v[26:27], s[10:11], 0, v[38:39]
	global_load_dwordx4 v[30:33], v[22:23], off
	global_load_dwordx4 v[42:45], v[34:35], off
	v_lshl_add_u64 v[22:23], s[42:43], 0, v[38:39]
	v_lshl_add_u64 v[34:35], s[82:83], 0, v[38:39]
	global_load_dwordx4 v[22:25], v[22:23], off
	v_lshl_add_u64 v[38:39], s[84:85], 0, v[38:39]
	global_load_dwordx4 v[34:37], v[34:35], off
	s_waitcnt vmcnt(6)
	v_mov_b32_e32 v64, v10
	global_load_dwordx4 v[26:29], v[26:27], off
	v_mov_b32_e32 v65, v6
	global_load_dwordx4 v[38:41], v[38:39], off
	v_readlane_b32 s0, v252, 18
	v_readlane_b32 s100, v252, 18
	v_readlane_b32 s101, v252, 19
	v_readlane_b32 s1, v252, 19
	v_add_u32_e32 v0, s29, v0
	s_waitcnt vmcnt(7)
	v_mov_b32_e32 v62, v58
	s_waitcnt vmcnt(6)
	v_mov_b32_e32 v63, v18
	v_mov_b32_e32 v18, v59
	s_waitcnt vmcnt(5)
	v_mov_b32_e32 v67, v30
	s_waitcnt vmcnt(4)
	v_mov_b32_e32 v66, v42
	v_pk_mul_f32 v[64:65], v[64:65], v[66:67]
	v_mov_b32_e32 v30, v43
	v_pk_fma_f32 v[52:53], v[52:53], v[62:63], v[64:65]
	s_waitcnt vmcnt(3)
	v_mov_b32_e32 v63, v22
	s_waitcnt vmcnt(2)
	v_mov_b32_e32 v62, v34
	v_pk_fma_f32 v[52:53], v[54:55], v[62:63], v[52:53]
	s_waitcnt vmcnt(1)
	v_mov_b32_e32 v55, v26
	v_mov_b32_e32 v22, v35
	s_waitcnt vmcnt(0)
	v_mov_b32_e32 v54, v38
	v_pk_add_f32 v[52:53], v[54:55], v[52:53]
	v_mov_b32_e32 v26, v39
	v_mul_f32_e32 v6, 0xbfb8aa3b, v53
	v_exp_f32_e32 v6, v6
	v_mov_b32_e32 v10, v44
	v_add_f32_e32 v6, 1.0, v6
	v_rcp_f32_e32 v6, v6
	s_nop 0
	v_mul_f32_e32 v6, v53, v6
	v_mul_f32_e32 v34, v52, v6
	v_mov_b32_e32 v6, v11
	v_pk_mul_f32 v[6:7], v[6:7], v[30:31]
	v_mov_b32_e32 v11, v32
	v_pk_fma_f32 v[2:3], v[2:3], v[18:19], v[6:7]
	v_mov_b32_e32 v7, v8
	v_pk_fma_f32 v[2:3], v[14:15], v[22:23], v[2:3]
	v_mov_b32_e32 v8, v13
	v_pk_add_f32 v[2:3], v[26:27], v[2:3]
	v_mov_b32_e32 v32, v45
	v_mul_f32_e32 v6, 0xbfb8aa3b, v3
	v_exp_f32_e32 v6, v6
	s_nop 0
	v_add_f32_e32 v6, 1.0, v6
	v_rcp_f32_e32 v6, v6
	s_nop 0
	v_mul_f32_e32 v3, v3, v6
	v_mov_b32_e32 v6, v12
	v_mul_f32_e32 v14, v2, v3
	v_mov_b32_e32 v2, v60
	v_mov_b32_e32 v3, v20
	v_pk_mul_f32 v[6:7], v[6:7], v[10:11]
	v_mov_b32_e32 v20, v61
	v_pk_fma_f32 v[2:3], v[48:49], v[2:3], v[6:7]
	v_mov_b32_e32 v6, v36
	v_mov_b32_e32 v7, v24
	v_pk_fma_f32 v[2:3], v[50:51], v[6:7], v[2:3]
	v_mov_b32_e32 v6, v40
	v_mov_b32_e32 v7, v28
	v_pk_add_f32 v[2:3], v[6:7], v[2:3]
	v_mov_b32_e32 v24, v37
	v_mul_f32_e32 v6, 0xbfb8aa3b, v3
	v_exp_f32_e32 v6, v6
	v_mov_b32_e32 v28, v41
	v_add_f32_e32 v6, 1.0, v6
	v_rcp_f32_e32 v6, v6
	s_nop 0
	v_mul_f32_e32 v3, v3, v6
	v_mul_f32_e32 v6, v2, v3
	v_pk_mul_f32 v[2:3], v[8:9], v[32:33]
	s_nop 0
	v_pk_fma_f32 v[2:3], v[4:5], v[20:21], v[2:3]
	s_nop 0
	v_pk_fma_f32 v[2:3], v[16:17], v[24:25], v[2:3]
	s_nop 0
	v_pk_add_f32 v[2:3], v[28:29], v[2:3]
	s_nop 0
	v_mul_f32_e32 v4, 0xbfb8aa3b, v3
	v_exp_f32_e32 v4, v4
	s_nop 0
	v_add_f32_e32 v4, 1.0, v4
	v_rcp_f32_e32 v4, v4
	s_nop 0
	v_mul_f32_e32 v3, v3, v4
	v_mov_b64_e32 v[4:5], s[0:1]
	s_movk_i32 s0, 0x2c00
	s_mov_b32 s0, 0x41fff
	s_nop 0
	v_cmp_lt_i32_e32 vcc, s0, v0
	v_mul_f32_e32 v3, v2, v3
	s_or_b64 s[96:97], vcc, s[96:97]
	v_cvt_pk_bf16_f32 v2, v34, v14
	v_cvt_pk_bf16_f32 v3, v6, v3
	v_lshrrev_b32_e32 v4, 8, v56
	v_mul_u32_u24_e32 v4, 0x2c0000, v4
	v_lshrrev_b32_e32 v5, 6, v46
	v_lshl_add_u32 v4, v5, 15, v4
	v_bfe_u32 v5, v46, 5, 1
	v_lshl_add_u32 v4, v5, 10, v4
	v_and_b32_e32 v5, 31, v46
	v_lshlrev_b32_e32 v5, 1, v5
	v_xor_b32_e32 v6, 32, v5
	v_add_u32_e32 v6, 0x7bc0, v6
	v_and_b32_e32 v34, 1, v56
	v_cmp_eq_u32_e32 vcc, 1, v34
	v_cndmask_b32_e32 v5, v5, v6, vcc
	v_add_u32_e32 v4, v4, v5
	global_store_dwordx2 v4, v[2:3], s[100:101]
	s_andn2_b64 exec, exec, s[96:97]
	s_cbranch_execz .LBB0_152

; #define PG8_WAIT_V(n) asm volatile("s_waitcnt vmcnt(" #n ")" ::: "memory")
; #define PG8_BAR __builtin_amdgcn_s_barrier()
; template <class Epi, class Sched, bool ALIGN_EPI = false, bool SP2 = false>
; __device__ __forceinline__ void gemm_phase(PG8_LAS unsigned char* lds, const Gemm g, const Sched& S, const Epi& E) {
;     ...
;     for (int i = 0; i < 2; ++i) { int R, C; stage_rc(tid * 16 + i * 8192, R, C); const int Rb = Epi::PERM ? ((R & ~31) + perm32(R & 31)) : R;
;         const int Ra = Epi::APERM ? ((R & ~63) + ((R & 15) << 2) + ((R >> 4) & 3)) : R;
;         voffA[i] = (unsigned)(Ra * K + C) * 2u; voffB[i] = (unsigned)(Rb * K + C) * 2u; }
;     const size_t kstep = (size_t)(BK * 2);
;     const size_t hstep = (size_t)HALF * K * 2;
;     const size_t tstep = 2 * hstep;
;     const unsigned ldsw = (unsigned)wid * 1024u;
;     const int aoff = lds_byte(wr * 64 + fr, fq * 8), boff = lds_byte(wc * 32 + fr, fq * 8);
;     ...
;     Unit cur, nxt; int ui = 0;
;     if (!S.next(0, cur)) return;
;     f32x4 acc[2][2][4][2];
; #pragma unroll
;     for (int a = 0; a < 2; ++a)
; #pragma unroll
;         for (int b = 0; b < 2; ++b)
; #pragma unroll
;             for (int m = 0; m < 4; ++m)
; #pragma unroll
;                 for (int n = 0; n < 2; ++n) acc[a][b][m][n] = (f32x4){0.f, 0.f, 0.f, 0.f};
;     bf16x8 At[4][2], B0[2][2], B1[2][2];
;     const char* cA = (const char*)g.A + (size_t)cur.pm * tstep; const char* cB = (const char*)g.Bt + (size_t)cur.pn * tstep;
;     S.a_ready(cur);
;     if constexpr (SP2) {
;         PG8_STAGE(PG8_SB(0, 0), cB, voffB); PG8_STAGE(PG8_SB(0, 1), cB + hstep, voffB); PG8_STAGE(PG8_SA(0, 0), cA, voffA); PG8_STAGE(PG8_SA(0, 1), cA + hstep, voffA);
;         if (wr == 1) PG8_BAR;
;         PG8_WAIT_V(2); PG8_BAR;
;         PG8_STAGE(PG8_SB(1, 0), cB + kstep, voffB); PG8_STAGE(PG8_SA(1, 0), cA + kstep, voffA); PG8_STAGE(PG8_SB(1, 1), cB + hstep + kstep, voffB);
;         PG8_WAIT_V(6); PG8_BAR;
;     } else {
;         PG8_STAGE(PG8_SB(0, 0), cB, voffB); PG8_STAGE(PG8_SA(0, 0), cA, voffA); PG8_STAGE(PG8_SB(0, 1), cB + hstep, voffB); PG8_STAGE(PG8_SA(0, 1), cA + hstep, voffA);
;         if (wr == 1) PG8_BAR;
;         PG8_WAIT_V(4); PG8_BAR;
;         PG8_STAGE(PG8_SB(1, 0), cB + kstep, voffB); PG8_STAGE(PG8_SA(1, 0), cA + kstep, voffA); PG8_STAGE(PG8_SB(1, 1), cB + hstep + kstep, voffB);
;         PG8_WAIT_V(6); PG8_BAR;
.LBB0_162:
	s_andn2_b64 vcc, exec, s[4:5]
	s_cbranch_vccnz .LBB0_253
	s_waitcnt lgkmcnt(0)
	v_bfe_i32 v3, v20, 27, 1
	v_lshlrev_b32_e32 v2, 4, v20
	v_lshrrev_b32_e32 v3, 22, v3
	v_add_u32_e32 v3, v2, v3
	v_and_b32_e32 v3, 0xfffffc00, v3
	v_sub_u32_e32 v3, v2, v3
	v_ashrrev_i32_e32 v0, 31, v20
	v_lshrrev_b32_e32 v4, 4, v3
	v_lshrrev_b32_e32 v0, 26, v0
	v_bitop3_b32 v3, v4, v3, 32 bitop3:0x6c
	v_add_u32_e32 v0, v20, v0
	v_ashrrev_i32_e32 v5, 31, v3
	v_ashrrev_i32_e32 v0, 6, v0
	v_lshrrev_b32_e32 v5, 26, v5
	v_lshlrev_b32_e32 v4, 3, v0
	v_add_u32_e32 v5, v3, v5
	v_and_b32_e32 v4, -16, v4
	v_ashrrev_i32_e32 v6, 6, v5
	v_lshlrev_b32_e32 v0, 5, v0
	v_add_u32_e32 v4, v6, v4
	v_and_b32_e32 v14, 32, v0
	v_and_b32_e32 v0, 0xc0, v5
	v_sub_u32_e32 v0, v3, v0
	v_lshlrev_b32_e32 v3, 1, v4
	v_lshrrev_b32_e32 v5, 2, v4
	v_and_b32_e32 v6, 3, v6
	s_mov_b32 s5, 0x7fffffe0
	v_ashrrev_i16_sdwa v0, v244, sext(v0) dst_sel:DWORD dst_unused:UNUSED_PAD src0_sel:DWORD src1_sel:BYTE_0
	v_and_b32_e32 v3, 24, v3
	v_and_b32_e32 v5, 4, v5
	v_and_or_b32 v6, v4, s5, v6
	v_bfe_i32 v15, v0, 0, 16
	v_or3_b32 v3, v6, v5, v3
	v_add_u32_e32 v0, v14, v15
	v_mul_lo_u32 v16, v4, s11
	v_mul_lo_u32 v3, v3, s11
	v_add_u32_e32 v2, 0x2000, v2
	v_add_lshl_u32 v194, v0, v16, 1
	s_movk_i32 s98, 0x80
	s_mov_b32 s99, 0
	s_lshl_b32 s100, s11, 8
	s_mov_b32 s101, 0
	s_cmp_lg_u32 s11, 0x1600
	s_cbranch_scc1 .Ltl_a
	s_mov_b32 s98, 0x8000
	s_movk_i32 s100, 0x4000
	v_lshlrev_b32_e32 v194, 4, v246
.Ltl_a:
	v_add_lshl_u32 v0, v3, v0, 1
	v_ashrrev_i32_e32 v3, 31, v2
	v_lshrrev_b32_e32 v3, 22, v3
	v_add_u32_e32 v3, v2, v3
	v_ashrrev_i32_e32 v3, 10, v3
	v_mul_i32_i24_e32 v4, 0x400, v3
	v_sub_u32_e32 v2, v2, v4
	v_lshrrev_b32_e32 v4, 4, v2
	v_bitop3_b32 v2, v4, v2, 32 bitop3:0x6c
	v_ashrrev_i32_e32 v5, 31, v2
	v_lshrrev_b32_e32 v5, 26, v5
	v_lshlrev_b32_e32 v4, 3, v3
	v_add_u32_e32 v5, v2, v5
	v_and_b32_e32 v4, -16, v4
	v_ashrrev_i32_e32 v6, 6, v5
	v_add_u32_e32 v4, v6, v4
	v_and_b32_e32 v6, 3, v6
	v_lshlrev_b32_e32 v3, 5, v3
	v_and_or_b32 v6, v4, s5, v6
	s_ashr_i32 s5, s67, 6
	s_lshl_b32 s29, s11, 9
	s_ashr_i32 s4, s67, 8
	v_and_b32_e32 v17, 32, v3
	v_and_b32_e32 v3, 0xc0, v5
	s_lshl_b32 s58, s11, 8
	s_lshl_b32 s80, s5, 10
	s_mul_i32 s7, s29, s83
	v_sub_u32_e32 v2, v2, v3
	v_lshlrev_b32_e32 v3, 1, v4
	v_lshrrev_b32_e32 v5, 2, v4
	s_mul_hi_i32 s6, s29, s83
	s_add_u32 s8, s20, s7
	v_ashrrev_i16_sdwa v2, v244, sext(v2) dst_sel:DWORD dst_unused:UNUSED_PAD src0_sel:DWORD src1_sel:BYTE_0
	v_and_b32_e32 v3, 24, v3
	v_and_b32_e32 v5, 4, v5
	s_addc_u32 s9, s21, s6
	s_add_i32 s81, s80, 0
	v_bfe_i32 v18, v2, 0, 16
	v_or3_b32 v3, v6, v5, v3
	s_add_i32 m0, s81, 0x10000
	v_add_u32_e32 v2, v17, v18
	v_mul_lo_u32 v3, v3, s11
	global_load_lds_dwordx4 v0, s[8:9]
	s_add_i32 m0, s81, 0x12000
	v_add_lshl_u32 v198, v3, v2, 1
	s_add_u32 s6, s8, s58
	global_load_lds_dwordx4 v198, s[8:9]
	s_addc_u32 s7, s9, 0
	s_add_i32 m0, s81, 0x14000
	s_mul_i32 s69, s29, s66
	v_mov_b32_e32 v199, v1
	global_load_lds_dwordx4 v0, s[6:7]
	s_add_i32 m0, s81, 0x16000
	s_mul_hi_i32 s12, s29, s66
	v_lshl_add_u64 v[6:7], s[6:7], 0, v[0:1]
	v_lshl_add_u64 v[8:9], s[6:7], 0, v[198:199]
	global_load_lds_dwordx4 v198, s[6:7]
	s_add_u32 s6, s40, s69
	s_addc_u32 s7, s41, s12
	s_add_i32 s70, s81, 0x2000
	v_mul_lo_u32 v19, v4, s11
	s_mov_b32 m0, s81
	s_add_u32 s84, s6, s100
	v_add_lshl_u32 v196, v2, v19, 1
	global_load_lds_dwordx4 v194, s[6:7]
	s_mov_b32 m0, s70
	s_addc_u32 s85, s7, 0
	s_add_i32 s71, s81, 0x4000
	s_cmp_lg_u32 s98, 0x8000
	s_cbranch_scc1 .Ltl_b
	v_add_u32_e32 v196, 0x2000, v194
.Ltl_b:
	global_load_lds_dwordx4 v196, s[6:7]
	s_mov_b32 m0, s71
	s_add_i32 s12, s81, 0x6000
	global_load_lds_dwordx4 v194, s[84:85]
	s_mov_b32 m0, s12
	s_cmp_eq_u32 s4, 1
	global_load_lds_dwordx4 v196, s[84:85]
	s_cselect_b64 s[16:17], -1, 0
	v_mov_b32_e32 v195, v1
	v_mov_b32_e32 v197, v1
	v_writelane_b32 v254, s16, 48
	v_lshl_add_u64 v[2:3], s[8:9], 0, v[0:1]
	v_lshl_add_u64 v[4:5], s[8:9], 0, v[198:199]
	v_lshl_add_u64 v[10:11], s[6:7], 0, v[194:195]
	v_lshl_add_u64 v[12:13], s[6:7], 0, v[196:197]
	v_writelane_b32 v254, s17, 49
	s_cmp_lg_u32 s4, 1
	s_cbranch_scc1 .LBB0_165
	s_barrier
.LBB0_165:
	v_readlane_b32 s16, v254, 36
	v_readlane_b32 s17, v254, 37
	s_cmp_lt_i32 s16, 26
	s_cselect_b64 s[84:85], -1, 0
	v_readlane_b32 s16, v252, 37
	s_or_b64 s[0:1], s[84:85], s[0:1]
	v_readlane_b32 s17, v252, 38
	s_and_b64 s[0:1], s[16:17], s[0:1]
	s_and_b64 s[0:1], s[0:1], exec
	s_cselect_b32 s82, s13, -1
	s_lshl_b32 s0, s4, 6
	v_and_b32_e32 v21, 48, v20
	v_lshlrev_b32_e32 v22, 6, v20
	s_movk_i32 s1, 0x3c0
	v_lshlrev_b32_e32 v20, 2, v20
	v_readlane_b32 s18, v254, 38
	v_readlane_b32 s19, v254, 39
	s_and_b32 s43, s5, 3
	v_writelane_b32 v254, s0, 42
	s_lshl_b32 s0, s4, 13
	v_and_or_b32 v21, v22, s1, v21
	v_and_b32_e32 v20, 32, v20
	v_bitop3_b32 v22, v21, s0, v20 bitop3:0xde
	s_lshl_b32 s0, s43, 12
	v_bitop3_b32 v248, v21, s0, v20 bitop3:0xde
	s_mul_i32 s0, s37, 0xc000
	s_add_i32 s0, s0, s10
	s_ashr_i32 s1, s0, 31
	s_lshr_b32 s69, s11, 6
	s_lshl_b32 s36, s43, 5
	s_lshl_b64 s[0:1], s[0:1], 3
	s_add_u32 s44, s34, s0
	s_addc_u32 s45, s35, s1
	s_add_i32 m0, s81, 0x18000
	v_lshl_add_u64 v[2:3], v[2:3], 0, s[92:93]
	s_waitcnt vmcnt(2)
	s_barrier
	global_load_lds_dwordx4 v[2:3], off
	v_lshl_add_u64 v[2:3], v[4:5], 0, s[92:93]
	s_add_i32 m0, s81, 0x1a000
	s_add_i32 s10, s81, 0x8000
	global_load_lds_dwordx4 v[2:3], off
	v_lshl_add_u64 v[2:3], v[10:11], 0, s[98:99]
	s_mov_b32 m0, s10
	s_add_i32 s11, s81, 0xa000
	global_load_lds_dwordx4 v[2:3], off
	v_lshl_add_u64 v[2:3], v[12:13], 0, s[98:99]
	s_mov_b32 m0, s11
	s_add_i32 s13, s69, -2
	global_load_lds_dwordx4 v[2:3], off
	s_add_i32 m0, s81, 0x1c000
	v_lshl_add_u64 v[2:3], v[6:7], 0, s[92:93]
	global_load_lds_dwordx4 v[2:3], off
	v_lshl_add_u64 v[2:3], v[8:9], 0, s[92:93]
	s_add_i32 m0, s81, 0x1e000
	s_cmpk_lt_u32 s67, 0x100
	global_load_lds_dwordx4 v[2:3], off
	s_cselect_b64 s[46:47], -1, 0
	s_ashr_i32 s39, s23, 31
	s_cmp_gt_i32 s82, -1
	s_cselect_b64 s[48:49], -1, 0
	s_mul_hi_u32 s4, s82, 0x6000
	s_mul_i32 s5, s82, 0x6000
	s_and_b64 s[0:1], s[48:49], exec
	s_cselect_b32 s1, s4, 0
	s_cselect_b32 s0, s5, 0
	s_lshl_b64 s[0:1], s[0:1], 2
	v_readlane_b32 s16, v252, 52
	v_readlane_b32 s17, v252, 53
	s_add_u32 s50, s16, s0
	s_addc_u32 s51, s17, s1
	v_readlane_b32 s0, v252, 54
	v_add_u32_e32 v2, v16, v14
	s_add_u32 s0, s0, s5
	v_add_lshl_u32 v2, v2, v15, 1
	v_mov_b32_e32 v3, v1
	s_waitcnt vmcnt(6)
	v_writelane_b32 v254, s0, 44
	v_readlane_b32 s0, v252, 55
	v_lshl_add_u64 v[200:201], s[58:59], 0, v[2:3]
	v_add_u32_e32 v2, v19, v17
	s_addc_u32 s0, s0, s4
	v_add_lshl_u32 v2, v2, v18, 1
	s_mov_b32 s82, 0
	v_writelane_b32 v254, s0, 50
	v_lshl_add_u64 v[210:211], s[58:59], 0, v[2:3]
	s_cmp_lg_u32 s98, 0x8000
	s_cbranch_scc1 .Ltl_c
	v_add_u32_e32 v200, 0x4000, v194
	v_mov_b32_e32 v201, 0
	v_add_u32_e32 v210, 0x4000, v196
	v_mov_b32_e32 v211, 0
.Ltl_c:
	v_add_u32_e32 v249, 0, v22
	v_readlane_b32 s16, v252, 11
	s_barrier
	s_branch .LBB0_168

; #define PG8_STAGE(bufoff, gbase, voff) do { _Pragma("unroll") for (int _i = 0; _i < 2; ++_i) \
;         __builtin_amdgcn_global_load_lds((const unsigned*)((const char*)(gbase) + (voff)[_i]), (PG8_LAS unsigned*)(lds + (bufoff) + ldsw + _i * 8192), 16, 0, 0); } while (0)
; #define PG8_LDA(dst, b, h) do { _Pragma("unroll") for (int m = 0; m < 4; ++m) _Pragma("unroll") for (int k = 0; k < 2; ++k) dst[m][k] = *(const PG8_LAS bf16x8*)(lds + PG8_SA(b, h) + aoff + m * 2048 + k * 1024); } while (0)
; #define PG8_LDB(dst, b, h) do { _Pragma("unroll") for (int n = 0; n < 2; ++n) _Pragma("unroll") for (int k = 0; k < 2; ++k) dst[n][k] = *(const PG8_LAS bf16x8*)(lds + PG8_SB(b, h) + boff + n * 2048 + k * 1024); } while (0)
; #define PG8_WAIT_V(n) asm volatile("s_waitcnt vmcnt(" #n ")" ::: "memory")
; #define PG8_WAIT_L(n) asm volatile("s_waitcnt lgkmcnt(" #n ")" ::: "memory")
; #define PG8_BAR __builtin_amdgcn_s_barrier()
; #define PG8_SCHED __builtin_amdgcn_sched_barrier(0)
; template <class Epi, class Sched, bool ALIGN_EPI = false, bool SP2 = false>
; __device__ __forceinline__ void gemm_phase(PG8_LAS unsigned char* lds, const Gemm g, const Sched& S, const Epi& E) {
;     ...
;         const bool has_next = S.next(ui + 1, nxt);
;         const char* nA = has_next ? (const char*)g.A + (size_t)nxt.pm * tstep : cA; const char* nB = has_next ? (const char*)g.Bt + (size_t)nxt.pn * tstep : cB;
;         for (int t = 0; t < nt; t += 2) {
;             const bool last = (t == nt - 2);
;             const char* a1 = cA + (size_t)(t + 1) * kstep;
;             const char* a2 = last ? nA : cA + (size_t)(t + 2) * kstep; const char* b2 = last ? nB : cB + (size_t)(t + 2) * kstep;
;             const char* a3 = a2 + kstep; const char* b3 = b2 + kstep;
;             if (last && has_next) S.a_ready(nxt);
;             if constexpr (SP2) {
;             PG8_LDB(B0, 0, 0); PG8_LDB(B1, 0, 1); PG8_SCHED; PG8_LDA(At, 0, 0); PG8_STAGE(PG8_SA(1, 1), a1 + hstep, voffA);
;             PG8_WAIT_V(8); PG8_WAIT_L(0); PG8_BAR; PG8_MMA(0, 0, At, B0); PG8_MMA(0, 1, At, B1); PG8_BAR; PG8_SCHED;
;             PG8_LDA(At, 0, 1); PG8_STAGE(PG8_SB(0, 0), b2, voffB); PG8_STAGE(PG8_SB(0, 1), b2 + hstep, voffB); PG8_STAGE(PG8_SA(0, 0), a2, voffA);
;             PG8_WAIT_V(8); PG8_WAIT_L(0); PG8_BAR; PG8_MMA(1, 0, At, B0); PG8_MMA(1, 1, At, B1); PG8_BAR; PG8_SCHED;
.LBB0_174:
	s_add_u32 s6, s6, s98
	s_addc_u32 s7, s7, 0
	s_add_u32 s67, s8, 0x100
	s_addc_u32 s85, s9, 0
	s_mov_b32 s8, 0
	s_waitcnt vmcnt(0)
.Lpeel175:
	s_add_i32 vcc_lo, s8, 2
	s_add_u32 s4, s6, s98
	s_addc_u32 s5, s7, 0
	s_add_i32 vcc_hi, 0, 0x10000
	s_cmp_eq_u32 s13, s8
	s_cselect_b32 s9, s1, s5
	s_cselect_b32 s8, s0, s4
	s_cselect_b32 s5, s97, s85
	s_cselect_b32 s4, s96, s67
	s_add_i32 s84, 0, 0x14000
	v_add_u32_e32 v122, vcc_hi, v248
	v_add_u32_e32 v154, s84, v248
	ds_read_b128 v[98:101], v122
	ds_read_b128 v[102:105], v122 offset:1024
	ds_read_b128 v[114:117], v122 offset:2048
	ds_read_b128 v[122:125], v122 offset:3072
	ds_read_b128 v[130:133], v154
	ds_read_b128 v[138:141], v154 offset:1024
	ds_read_b128 v[146:149], v154 offset:2048
	ds_read_b128 v[154:157], v154 offset:3072
	v_lshl_add_u64 v[206:207], s[6:7], 0, v[200:201]
	s_add_i32 m0, s81, 0xc000
	ds_read_b128 v[162:165], v249
	ds_read_b128 v[166:169], v249 offset:1024
	ds_read_b128 v[170:173], v249 offset:2048
	ds_read_b128 v[174:177], v249 offset:3072
	ds_read_b128 v[178:181], v249 offset:4096
	ds_read_b128 v[182:185], v249 offset:5120
	ds_read_b128 v[186:189], v249 offset:6144
	ds_read_b128 v[190:193], v249 offset:7168
	global_load_lds_dwordx4 v[206:207], off
	v_lshl_add_u64 v[206:207], s[6:7], 0, v[210:211]
	s_add_i32 m0, s81, 0xe000
	s_nop 0
	global_load_lds_dwordx4 v[206:207], off
	s_waitcnt vmcnt(8)
	s_waitcnt lgkmcnt(0)
	s_barrier
	s_setprio 1
	s_waitcnt lgkmcnt(0)
	v_mfma_f32_16x16x32_bf16 v[158:161], v[98:101], v[162:165], 0
	v_mfma_f32_16x16x32_bf16 v[150:153], v[114:117], v[162:165], 0
	v_mfma_f32_16x16x32_bf16 v[118:121], v[114:117], v[170:173], 0
	v_mfma_f32_16x16x32_bf16 v[126:129], v[98:101], v[170:173], 0
	v_mfma_f32_16x16x32_bf16 v[94:97], v[98:101], v[178:181], 0
	v_mfma_f32_16x16x32_bf16 v[90:93], v[114:117], v[178:181], 0
	v_mfma_f32_16x16x32_bf16 v[74:77], v[114:117], v[186:189], 0
	v_mfma_f32_16x16x32_bf16 v[78:81], v[98:101], v[186:189], 0
	v_mfma_f32_16x16x32_bf16 v[158:161], v[102:105], v[166:169], v[158:161]
	v_mfma_f32_16x16x32_bf16 v[150:153], v[122:125], v[166:169], v[150:153]
	v_mfma_f32_16x16x32_bf16 v[118:121], v[122:125], v[174:177], v[118:121]
	v_mfma_f32_16x16x32_bf16 v[126:129], v[102:105], v[174:177], v[126:129]
	v_mfma_f32_16x16x32_bf16 v[94:97], v[102:105], v[182:185], v[94:97]
	v_mfma_f32_16x16x32_bf16 v[90:93], v[122:125], v[182:185], v[90:93]
	v_mfma_f32_16x16x32_bf16 v[74:77], v[122:125], v[190:193], v[74:77]
	v_mfma_f32_16x16x32_bf16 v[78:81], v[102:105], v[190:193], v[78:81]
	s_setprio 0
	s_setprio 1
	v_mfma_f32_16x16x32_bf16 v[142:145], v[130:133], v[162:165], 0
	v_mfma_f32_16x16x32_bf16 v[134:137], v[146:149], v[162:165], 0
	v_mfma_f32_16x16x32_bf16 v[106:109], v[146:149], v[170:173], 0
	v_mfma_f32_16x16x32_bf16 v[110:113], v[130:133], v[170:173], 0
	v_mfma_f32_16x16x32_bf16 v[86:89], v[130:133], v[178:181], 0
	v_mfma_f32_16x16x32_bf16 v[82:85], v[146:149], v[178:181], 0
	v_mfma_f32_16x16x32_bf16 v[66:69], v[146:149], v[186:189], 0
	v_mfma_f32_16x16x32_bf16 v[70:73], v[130:133], v[186:189], 0
	v_mfma_f32_16x16x32_bf16 v[142:145], v[138:141], v[166:169], v[142:145]
	v_mfma_f32_16x16x32_bf16 v[134:137], v[154:157], v[166:169], v[134:137]
	v_mfma_f32_16x16x32_bf16 v[106:109], v[154:157], v[174:177], v[106:109]
	v_mfma_f32_16x16x32_bf16 v[110:113], v[138:141], v[174:177], v[110:113]
	v_mfma_f32_16x16x32_bf16 v[86:89], v[138:141], v[182:185], v[86:89]
	v_mfma_f32_16x16x32_bf16 v[82:85], v[154:157], v[182:185], v[82:85]
	v_mfma_f32_16x16x32_bf16 v[66:69], v[154:157], v[190:193], v[66:69]
	v_mfma_f32_16x16x32_bf16 v[70:73], v[138:141], v[190:193], v[70:73]
	s_setprio 0
	s_barrier
	s_add_i32 vcc_hi, vcc_hi, s80
	v_lshl_add_u64 v[206:207], s[4:5], 0, v[0:1]
	s_mov_b32 m0, vcc_hi
	ds_read_b128 v[162:165], v249 offset:16384
	ds_read_b128 v[166:169], v249 offset:17408
	ds_read_b128 v[170:173], v249 offset:18432
	ds_read_b128 v[174:177], v249 offset:19456
	ds_read_b128 v[178:181], v249 offset:20480
	ds_read_b128 v[182:185], v249 offset:21504
	ds_read_b128 v[186:189], v249 offset:22528
	ds_read_b128 v[190:193], v249 offset:23552
	global_load_lds_dwordx4 v[206:207], off
	s_add_i32 m0, vcc_hi, 0x2000
	v_lshl_add_u64 v[212:213], s[4:5], 0, v[198:199]
	s_add_u32 s4, s4, s58
	s_addc_u32 s5, s5, 0
	s_add_i32 s84, s84, s80
	global_load_lds_dwordx4 v[212:213], off
	v_lshl_add_u64 v[214:215], s[4:5], 0, v[0:1]
	s_mov_b32 m0, s84
	v_lshl_add_u64 v[216:217], s[4:5], 0, v[198:199]
	global_load_lds_dwordx4 v[214:215], off
	s_add_i32 m0, s84, 0x2000
	v_lshl_add_u64 v[218:219], s[8:9], 0, v[194:195]
	global_load_lds_dwordx4 v[216:217], off
	s_mov_b32 m0, s81
	v_lshl_add_u64 v[220:221], s[8:9], 0, v[196:197]
	global_load_lds_dwordx4 v[218:219], off
	s_mov_b32 m0, s70
	s_nop 0
	global_load_lds_dwordx4 v[220:221], off
	s_waitcnt vmcnt(8)
	s_waitcnt lgkmcnt(0)
	s_barrier
; #define PG8_STAGE(bufoff, gbase, voff) do { _Pragma("unroll") for (int _i = 0; _i < 2; ++_i) \
;         __builtin_amdgcn_global_load_lds((const unsigned*)((const char*)(gbase) + (voff)[_i]), (PG8_LAS unsigned*)(lds + (bufoff) + ldsw + _i * 8192), 16, 0, 0); } while (0)
; #define PG8_LDA(dst, b, h) do { _Pragma("unroll") for (int m = 0; m < 4; ++m) _Pragma("unroll") for (int k = 0; k < 2; ++k) dst[m][k] = *(const PG8_LAS bf16x8*)(lds + PG8_SA(b, h) + aoff + m * 2048 + k * 1024); } while (0)
; #define PG8_LDB(dst, b, h) do { _Pragma("unroll") for (int n = 0; n < 2; ++n) _Pragma("unroll") for (int k = 0; k < 2; ++k) dst[n][k] = *(const PG8_LAS bf16x8*)(lds + PG8_SB(b, h) + boff + n * 2048 + k * 1024); } while (0)
; #define PG8_MMA(ai, bj, At, Bt) do { __builtin_amdgcn_s_setprio(1); _Pragma("unroll") for (int m = 0; m < 4; ++m) _Pragma("unroll") for (int n = 0; n < 2; ++n) _Pragma("unroll") for (int k = 0; k < 2; ++k) \
;         acc[ai][bj][m][n] = mma16<Epi::I8>(Bt[n][k], At[m][k], acc[ai][bj][m][n]); __builtin_amdgcn_s_setprio(0); } while (0)
; #define PG8_WAIT_V(n) asm volatile("s_waitcnt vmcnt(" #n ")" ::: "memory")
; #define PG8_WAIT_L(n) asm volatile("s_waitcnt lgkmcnt(" #n ")" ::: "memory")
; #define PG8_BAR __builtin_amdgcn_s_barrier()
; #define PG8_SCHED __builtin_amdgcn_sched_barrier(0)
; template <class Epi, class Sched, bool ALIGN_EPI = false, bool SP2 = false>
; __device__ __forceinline__ void gemm_phase(PG8_LAS unsigned char* lds, const Gemm g, const Sched& S, const Epi& E) {
;     ...
;             PG8_WAIT_V(8); PG8_WAIT_L(0); PG8_BAR; PG8_MMA(1, 0, At, B0); PG8_MMA(1, 1, At, B1); PG8_BAR; PG8_SCHED;
;             PG8_LDB(B0, 1, 0); PG8_LDB(B1, 1, 1); PG8_SCHED; PG8_LDA(At, 1, 0); PG8_STAGE(PG8_SA(0, 1), a2 + hstep, voffA);
;             PG8_WAIT_V(8); PG8_WAIT_L(0); PG8_BAR; PG8_MMA(0, 0, At, B0); PG8_MMA(0, 1, At, B1); PG8_BAR; PG8_SCHED;
	s_setprio 1
	s_waitcnt lgkmcnt(0)
	v_mfma_f32_16x16x32_bf16 v[62:65], v[98:101], v[162:165], 0
	v_mfma_f32_16x16x32_bf16 v[58:61], v[114:117], v[162:165], 0
	v_mfma_f32_16x16x32_bf16 v[42:45], v[114:117], v[170:173], 0
	v_mfma_f32_16x16x32_bf16 v[46:49], v[98:101], v[170:173], 0
	v_mfma_f32_16x16x32_bf16 v[30:33], v[98:101], v[178:181], 0
	v_mfma_f32_16x16x32_bf16 v[26:29], v[114:117], v[178:181], 0
	v_mfma_f32_16x16x32_bf16 v[10:13], v[114:117], v[186:189], 0
	v_mfma_f32_16x16x32_bf16 v[14:17], v[98:101], v[186:189], 0
	v_mfma_f32_16x16x32_bf16 v[62:65], v[102:105], v[166:169], v[62:65]
	v_mfma_f32_16x16x32_bf16 v[58:61], v[122:125], v[166:169], v[58:61]
	v_mfma_f32_16x16x32_bf16 v[42:45], v[122:125], v[174:177], v[42:45]
	v_mfma_f32_16x16x32_bf16 v[46:49], v[102:105], v[174:177], v[46:49]
	v_mfma_f32_16x16x32_bf16 v[30:33], v[102:105], v[182:185], v[30:33]
	v_mfma_f32_16x16x32_bf16 v[26:29], v[122:125], v[182:185], v[26:29]
	v_mfma_f32_16x16x32_bf16 v[10:13], v[122:125], v[190:193], v[10:13]
	v_mfma_f32_16x16x32_bf16 v[14:17], v[102:105], v[190:193], v[14:17]
	s_setprio 0
	s_setprio 1
	v_mfma_f32_16x16x32_bf16 v[54:57], v[130:133], v[162:165], 0
	v_mfma_f32_16x16x32_bf16 v[50:53], v[146:149], v[162:165], 0
	v_mfma_f32_16x16x32_bf16 v[34:37], v[146:149], v[170:173], 0
	v_mfma_f32_16x16x32_bf16 v[38:41], v[130:133], v[170:173], 0
	v_mfma_f32_16x16x32_bf16 v[22:25], v[130:133], v[178:181], 0
	v_mfma_f32_16x16x32_bf16 v[18:21], v[146:149], v[178:181], 0
	v_mfma_f32_16x16x32_bf16 v[2:5], v[146:149], v[186:189], 0
	v_mfma_f32_16x16x32_bf16 v[6:9], v[130:133], v[186:189], 0
	v_mfma_f32_16x16x32_bf16 v[54:57], v[138:141], v[166:169], v[54:57]
	v_mfma_f32_16x16x32_bf16 v[50:53], v[154:157], v[166:169], v[50:53]
	v_mfma_f32_16x16x32_bf16 v[34:37], v[154:157], v[174:177], v[34:37]
	v_mfma_f32_16x16x32_bf16 v[38:41], v[138:141], v[174:177], v[38:41]
	v_mfma_f32_16x16x32_bf16 v[22:25], v[138:141], v[182:185], v[22:25]
	v_mfma_f32_16x16x32_bf16 v[18:21], v[154:157], v[182:185], v[18:21]
	v_mfma_f32_16x16x32_bf16 v[2:5], v[154:157], v[190:193], v[2:5]
	v_mfma_f32_16x16x32_bf16 v[6:9], v[138:141], v[190:193], v[6:9]
	s_setprio 0
	s_barrier
	s_add_i32 s84, 0, 0x18000
	s_add_i32 vcc_hi, 0, 0x1c000
	v_add_u32_e32 v122, s84, v248
	v_add_u32_e32 v154, vcc_hi, v248
	ds_read_b128 v[98:101], v122
	ds_read_b128 v[102:105], v122 offset:1024
	ds_read_b128 v[114:117], v122 offset:2048
	ds_read_b128 v[122:125], v122 offset:3072
	ds_read_b128 v[130:133], v154
	ds_read_b128 v[138:141], v154 offset:1024
	ds_read_b128 v[146:149], v154 offset:2048
	ds_read_b128 v[154:157], v154 offset:3072
	s_add_u32 s4, s8, s100
	s_addc_u32 s5, s9, 0
	s_mov_b32 m0, s71
	v_lshl_add_u64 v[222:223], s[4:5], 0, v[194:195]
	ds_read_b128 v[162:165], v249 offset:32768
	ds_read_b128 v[166:169], v249 offset:33792
	ds_read_b128 v[170:173], v249 offset:34816
	ds_read_b128 v[174:177], v249 offset:35840
	ds_read_b128 v[178:181], v249 offset:36864
	ds_read_b128 v[182:185], v249 offset:37888
	ds_read_b128 v[186:189], v249 offset:38912
	ds_read_b128 v[190:193], v249 offset:39936
	global_load_lds_dwordx4 v[222:223], off
	v_lshl_add_u64 v[222:223], s[4:5], 0, v[196:197]
	s_mov_b32 m0, s12
	s_nop 0
	global_load_lds_dwordx4 v[222:223], off
	s_waitcnt vmcnt(8)
	s_waitcnt lgkmcnt(0)
	s_barrier
	s_setprio 1
	s_waitcnt lgkmcnt(0)
	v_mfma_f32_16x16x32_bf16 v[158:161], v[98:101], v[162:165], v[158:161]
	v_mfma_f32_16x16x32_bf16 v[150:153], v[114:117], v[162:165], v[150:153]
	v_mfma_f32_16x16x32_bf16 v[118:121], v[114:117], v[170:173], v[118:121]
	v_mfma_f32_16x16x32_bf16 v[126:129], v[98:101], v[170:173], v[126:129]
	v_mfma_f32_16x16x32_bf16 v[94:97], v[98:101], v[178:181], v[94:97]
	v_mfma_f32_16x16x32_bf16 v[90:93], v[114:117], v[178:181], v[90:93]
	v_mfma_f32_16x16x32_bf16 v[74:77], v[114:117], v[186:189], v[74:77]
	v_mfma_f32_16x16x32_bf16 v[78:81], v[98:101], v[186:189], v[78:81]
	v_mfma_f32_16x16x32_bf16 v[158:161], v[102:105], v[166:169], v[158:161]
	v_mfma_f32_16x16x32_bf16 v[150:153], v[122:125], v[166:169], v[150:153]
	v_mfma_f32_16x16x32_bf16 v[118:121], v[122:125], v[174:177], v[118:121]
	v_mfma_f32_16x16x32_bf16 v[126:129], v[102:105], v[174:177], v[126:129]
	v_mfma_f32_16x16x32_bf16 v[94:97], v[102:105], v[182:185], v[94:97]
	v_mfma_f32_16x16x32_bf16 v[90:93], v[122:125], v[182:185], v[90:93]
	v_mfma_f32_16x16x32_bf16 v[74:77], v[122:125], v[190:193], v[74:77]
	v_mfma_f32_16x16x32_bf16 v[78:81], v[102:105], v[190:193], v[78:81]
	s_setprio 0
	s_setprio 1
	v_mfma_f32_16x16x32_bf16 v[142:145], v[130:133], v[162:165], v[142:145]
	v_mfma_f32_16x16x32_bf16 v[134:137], v[146:149], v[162:165], v[134:137]
	v_mfma_f32_16x16x32_bf16 v[106:109], v[146:149], v[170:173], v[106:109]
	v_mfma_f32_16x16x32_bf16 v[110:113], v[130:133], v[170:173], v[110:113]
	v_mfma_f32_16x16x32_bf16 v[86:89], v[130:133], v[178:181], v[86:89]
	v_mfma_f32_16x16x32_bf16 v[82:85], v[146:149], v[178:181], v[82:85]
	v_mfma_f32_16x16x32_bf16 v[66:69], v[146:149], v[186:189], v[66:69]
	v_mfma_f32_16x16x32_bf16 v[70:73], v[130:133], v[186:189], v[70:73]
	v_mfma_f32_16x16x32_bf16 v[142:145], v[138:141], v[166:169], v[142:145]
	v_mfma_f32_16x16x32_bf16 v[134:137], v[154:157], v[166:169], v[134:137]
	v_mfma_f32_16x16x32_bf16 v[106:109], v[154:157], v[174:177], v[106:109]
	v_mfma_f32_16x16x32_bf16 v[110:113], v[138:141], v[174:177], v[110:113]
	v_mfma_f32_16x16x32_bf16 v[86:89], v[138:141], v[182:185], v[86:89]
	v_mfma_f32_16x16x32_bf16 v[82:85], v[154:157], v[182:185], v[82:85]
	v_mfma_f32_16x16x32_bf16 v[66:69], v[154:157], v[190:193], v[66:69]
	v_mfma_f32_16x16x32_bf16 v[70:73], v[138:141], v[190:193], v[70:73]
	s_setprio 0
	s_barrier
; #define PG8_STAGE(bufoff, gbase, voff) do { _Pragma("unroll") for (int _i = 0; _i < 2; ++_i) \
;         __builtin_amdgcn_global_load_lds((const unsigned*)((const char*)(gbase) + (voff)[_i]), (PG8_LAS unsigned*)(lds + (bufoff) + ldsw + _i * 8192), 16, 0, 0); } while (0)
; #define PG8_LDA(dst, b, h) do { _Pragma("unroll") for (int m = 0; m < 4; ++m) _Pragma("unroll") for (int k = 0; k < 2; ++k) dst[m][k] = *(const PG8_LAS bf16x8*)(lds + PG8_SA(b, h) + aoff + m * 2048 + k * 1024); } while (0)
; #define PG8_LDB(dst, b, h) do { _Pragma("unroll") for (int n = 0; n < 2; ++n) _Pragma("unroll") for (int k = 0; k < 2; ++k) dst[n][k] = *(const PG8_LAS bf16x8*)(lds + PG8_SB(b, h) + boff + n * 2048 + k * 1024); } while (0)
; template <class Epi, class Sched, bool ALIGN_EPI = false, bool SP2 = false>
; __device__ __forceinline__ void gemm_phase(PG8_LAS unsigned char* lds, const Gemm g, const Sched& S, const Epi& E) {
;     ...
;         for (int t = 0; t < nt; t += 2) {
;             const bool last = (t == nt - 2);
;             const char* a1 = cA + (size_t)(t + 1) * kstep;
;             const char* a2 = last ? nA : cA + (size_t)(t + 2) * kstep; const char* b2 = last ? nB : cB + (size_t)(t + 2) * kstep;
;             const char* a3 = a2 + kstep; const char* b3 = b2 + kstep;
;             if (last && has_next) S.a_ready(nxt);
;             if constexpr (SP2) {
;             PG8_LDB(B0, 0, 0); PG8_LDB(B1, 0, 1); PG8_SCHED; PG8_LDA(At, 0, 0); PG8_STAGE(PG8_SA(1, 1), a1 + hstep, voffA);
;             PG8_WAIT_V(8); PG8_WAIT_L(0); PG8_BAR; PG8_MMA(0, 0, At, B0); PG8_MMA(0, 1, At, B1); PG8_BAR; PG8_SCHED;
;             PG8_LDA(At, 0, 1); PG8_STAGE(PG8_SB(0, 0), b2, voffB); PG8_STAGE(PG8_SB(0, 1), b2 + hstep, voffB); PG8_STAGE(PG8_SA(0, 0), a2, voffA);
;             PG8_WAIT_V(8); PG8_WAIT_L(0); PG8_BAR; PG8_MMA(1, 0, At, B0); PG8_MMA(1, 1, At, B1); PG8_BAR; PG8_SCHED;
;             PG8_LDB(B0, 1, 0); PG8_LDB(B1, 1, 1); PG8_SCHED; PG8_LDA(At, 1, 0); PG8_STAGE(PG8_SA(0, 1), a2 + hstep, voffA);
;             PG8_WAIT_V(8); PG8_WAIT_L(0); PG8_BAR; PG8_MMA(0, 0, At, B0); PG8_MMA(0, 1, At, B1); PG8_BAR; PG8_SCHED;
;             PG8_LDA(At, 1, 1); PG8_STAGE(PG8_SB(1, 0), b3, voffB); PG8_STAGE(PG8_SB(1, 1), b3 + hstep, voffB); PG8_STAGE(PG8_SA(1, 0), a3, voffA);
;             PG8_WAIT_V(8); PG8_WAIT_L(0); PG8_BAR; PG8_MMA(1, 0, At, B0); PG8_MMA(1, 1, At, B1); PG8_BAR; PG8_SCHED;
	s_add_i32 s4, s84, s80
	v_lshl_add_u64 v[206:207], v[206:207], 0, s[92:93]
	s_mov_b32 m0, s4
	ds_read_b128 v[162:165], v249 offset:49152
	ds_read_b128 v[166:169], v249 offset:50176
	ds_read_b128 v[170:173], v249 offset:51200
	ds_read_b128 v[174:177], v249 offset:52224
	ds_read_b128 v[178:181], v249 offset:53248
	ds_read_b128 v[182:185], v249 offset:54272
	ds_read_b128 v[186:189], v249 offset:55296
	ds_read_b128 v[190:193], v249 offset:56320
	global_load_lds_dwordx4 v[206:207], off
	v_lshl_add_u64 v[206:207], v[212:213], 0, s[92:93]
	s_add_i32 m0, s4, 0x2000
	s_add_i32 s4, vcc_hi, s80
	global_load_lds_dwordx4 v[206:207], off
	v_lshl_add_u64 v[206:207], v[214:215], 0, s[92:93]
	s_mov_b32 m0, s4
	s_nop 0
	global_load_lds_dwordx4 v[206:207], off
	v_lshl_add_u64 v[206:207], v[216:217], 0, s[92:93]
	s_add_i32 m0, s4, 0x2000
	s_nop 0
	global_load_lds_dwordx4 v[206:207], off
	v_lshl_add_u64 v[206:207], v[218:219], 0, s[98:99]
	s_mov_b32 m0, s10
	s_nop 0
	global_load_lds_dwordx4 v[206:207], off
	v_lshl_add_u64 v[206:207], v[220:221], 0, s[98:99]
	s_mov_b32 m0, s11
	s_nop 0
	global_load_lds_dwordx4 v[206:207], off
	s_waitcnt vmcnt(8)
	s_waitcnt lgkmcnt(0)
	s_barrier
	s_setprio 1
	s_waitcnt lgkmcnt(0)
	v_mfma_f32_16x16x32_bf16 v[62:65], v[98:101], v[162:165], v[62:65]
	v_mfma_f32_16x16x32_bf16 v[58:61], v[114:117], v[162:165], v[58:61]
	v_mfma_f32_16x16x32_bf16 v[42:45], v[114:117], v[170:173], v[42:45]
	v_mfma_f32_16x16x32_bf16 v[46:49], v[98:101], v[170:173], v[46:49]
	v_mfma_f32_16x16x32_bf16 v[30:33], v[98:101], v[178:181], v[30:33]
	v_mfma_f32_16x16x32_bf16 v[26:29], v[114:117], v[178:181], v[26:29]
	v_mfma_f32_16x16x32_bf16 v[10:13], v[114:117], v[186:189], v[10:13]
	v_mfma_f32_16x16x32_bf16 v[14:17], v[98:101], v[186:189], v[14:17]
	v_mfma_f32_16x16x32_bf16 v[62:65], v[102:105], v[166:169], v[62:65]
	v_mfma_f32_16x16x32_bf16 v[58:61], v[122:125], v[166:169], v[58:61]
	v_mfma_f32_16x16x32_bf16 v[42:45], v[122:125], v[174:177], v[42:45]
	v_mfma_f32_16x16x32_bf16 v[46:49], v[102:105], v[174:177], v[46:49]
	v_mfma_f32_16x16x32_bf16 v[30:33], v[102:105], v[182:185], v[30:33]
	v_mfma_f32_16x16x32_bf16 v[26:29], v[122:125], v[182:185], v[26:29]
	v_mfma_f32_16x16x32_bf16 v[10:13], v[122:125], v[190:193], v[10:13]
	v_mfma_f32_16x16x32_bf16 v[14:17], v[102:105], v[190:193], v[14:17]
	s_setprio 0
	s_setprio 1
	v_mfma_f32_16x16x32_bf16 v[54:57], v[130:133], v[162:165], v[54:57]
	v_mfma_f32_16x16x32_bf16 v[50:53], v[146:149], v[162:165], v[50:53]
	v_mfma_f32_16x16x32_bf16 v[34:37], v[146:149], v[170:173], v[34:37]
	v_mfma_f32_16x16x32_bf16 v[38:41], v[130:133], v[170:173], v[38:41]
	v_mfma_f32_16x16x32_bf16 v[22:25], v[130:133], v[178:181], v[22:25]
	v_mfma_f32_16x16x32_bf16 v[18:21], v[146:149], v[178:181], v[18:21]
	v_mfma_f32_16x16x32_bf16 v[2:5], v[146:149], v[186:189], v[2:5]
	v_mfma_f32_16x16x32_bf16 v[6:9], v[130:133], v[186:189], v[6:9]
	v_mfma_f32_16x16x32_bf16 v[54:57], v[138:141], v[166:169], v[54:57]
	v_mfma_f32_16x16x32_bf16 v[50:53], v[154:157], v[166:169], v[50:53]
	v_mfma_f32_16x16x32_bf16 v[34:37], v[154:157], v[174:177], v[34:37]
	v_mfma_f32_16x16x32_bf16 v[38:41], v[138:141], v[174:177], v[38:41]
	v_mfma_f32_16x16x32_bf16 v[22:25], v[138:141], v[182:185], v[22:25]
	v_mfma_f32_16x16x32_bf16 v[18:21], v[154:157], v[182:185], v[18:21]
	v_mfma_f32_16x16x32_bf16 v[2:5], v[154:157], v[190:193], v[2:5]
	v_mfma_f32_16x16x32_bf16 v[6:9], v[138:141], v[190:193], v[6:9]
	s_setprio 0
	s_barrier
	s_add_u32 s6, s6, s98
	s_addc_u32 s7, s7, 0
	s_add_u32 s6, s6, s98
	s_addc_u32 s7, s7, 0
	s_add_u32 s67, s67, 0x100
	s_addc_u32 s85, s85, 0
	s_cmp_ge_u32 vcc_lo, s69
	s_mov_b32 s8, vcc_lo
	s_cbranch_scc0 .LBB0_175
	s_branch .Lpeelx175
.LBB0_175:
	s_add_i32 vcc_lo, s8, 2
	s_add_u32 s4, s6, s98
	s_addc_u32 s5, s7, 0
	s_add_i32 vcc_hi, 0, 0x10000
	s_cmp_eq_u32 s13, s8
	s_cselect_b32 s9, s1, s5
	s_cselect_b32 s8, s0, s4
	s_cselect_b32 s5, s97, s85
	s_cselect_b32 s4, s96, s67
	s_add_i32 s84, 0, 0x14000
	v_add_u32_e32 v122, vcc_hi, v248
	v_add_u32_e32 v154, s84, v248
	ds_read_b128 v[98:101], v122
	ds_read_b128 v[102:105], v122 offset:1024
	ds_read_b128 v[114:117], v122 offset:2048
	ds_read_b128 v[122:125], v122 offset:3072
	ds_read_b128 v[130:133], v154
	ds_read_b128 v[138:141], v154 offset:1024
	ds_read_b128 v[146:149], v154 offset:2048
	ds_read_b128 v[154:157], v154 offset:3072
	v_lshl_add_u64 v[206:207], s[6:7], 0, v[200:201]
	s_add_i32 m0, s81, 0xc000
	ds_read_b128 v[162:165], v249
	ds_read_b128 v[166:169], v249 offset:1024
	ds_read_b128 v[170:173], v249 offset:2048
	ds_read_b128 v[174:177], v249 offset:3072
	ds_read_b128 v[178:181], v249 offset:4096
	ds_read_b128 v[182:185], v249 offset:5120
	ds_read_b128 v[186:189], v249 offset:6144
	ds_read_b128 v[190:193], v249 offset:7168
	global_load_lds_dwordx4 v[206:207], off
	v_lshl_add_u64 v[206:207], s[6:7], 0, v[210:211]
	s_add_i32 m0, s81, 0xe000
	s_nop 0
	global_load_lds_dwordx4 v[206:207], off
	s_waitcnt vmcnt(8)
	s_waitcnt lgkmcnt(0)
	s_barrier
; #define PG8_STAGE(bufoff, gbase, voff) do { _Pragma("unroll") for (int _i = 0; _i < 2; ++_i) \
;         __builtin_amdgcn_global_load_lds((const unsigned*)((const char*)(gbase) + (voff)[_i]), (PG8_LAS unsigned*)(lds + (bufoff) + ldsw + _i * 8192), 16, 0, 0); } while (0)
; #define PG8_LDA(dst, b, h) do { _Pragma("unroll") for (int m = 0; m < 4; ++m) _Pragma("unroll") for (int k = 0; k < 2; ++k) dst[m][k] = *(const PG8_LAS bf16x8*)(lds + PG8_SA(b, h) + aoff + m * 2048 + k * 1024); } while (0)
; #define PG8_LDB(dst, b, h) do { _Pragma("unroll") for (int n = 0; n < 2; ++n) _Pragma("unroll") for (int k = 0; k < 2; ++k) dst[n][k] = *(const PG8_LAS bf16x8*)(lds + PG8_SB(b, h) + boff + n * 2048 + k * 1024); } while (0)
; #define PG8_MMA(ai, bj, At, Bt) do { __builtin_amdgcn_s_setprio(1); _Pragma("unroll") for (int m = 0; m < 4; ++m) _Pragma("unroll") for (int n = 0; n < 2; ++n) _Pragma("unroll") for (int k = 0; k < 2; ++k) \
;         acc[ai][bj][m][n] = mma16<Epi::I8>(Bt[n][k], At[m][k], acc[ai][bj][m][n]); __builtin_amdgcn_s_setprio(0); } while (0)
; #define PG8_WAIT_V(n) asm volatile("s_waitcnt vmcnt(" #n ")" ::: "memory")
; #define PG8_WAIT_L(n) asm volatile("s_waitcnt lgkmcnt(" #n ")" ::: "memory")
; #define PG8_BAR __builtin_amdgcn_s_barrier()
; #define PG8_SCHED __builtin_amdgcn_sched_barrier(0)
; template <class Epi, class Sched, bool ALIGN_EPI = false, bool SP2 = false>
; __device__ __forceinline__ void gemm_phase(PG8_LAS unsigned char* lds, const Gemm g, const Sched& S, const Epi& E) {
;     ...
;             PG8_LDB(B0, 0, 0); PG8_LDB(B1, 0, 1); PG8_SCHED; PG8_LDA(At, 0, 0); PG8_STAGE(PG8_SA(1, 1), a1 + hstep, voffA);
;             PG8_WAIT_V(8); PG8_WAIT_L(0); PG8_BAR; PG8_MMA(0, 0, At, B0); PG8_MMA(0, 1, At, B1); PG8_BAR; PG8_SCHED;
;             PG8_LDA(At, 0, 1); PG8_STAGE(PG8_SB(0, 0), b2, voffB); PG8_STAGE(PG8_SB(0, 1), b2 + hstep, voffB); PG8_STAGE(PG8_SA(0, 0), a2, voffA);
;             PG8_WAIT_V(8); PG8_WAIT_L(0); PG8_BAR; PG8_MMA(1, 0, At, B0); PG8_MMA(1, 1, At, B1); PG8_BAR; PG8_SCHED;
	s_setprio 1
	s_waitcnt lgkmcnt(0)
	v_mfma_f32_16x16x32_bf16 v[158:161], v[98:101], v[162:165], v[158:161]
	v_mfma_f32_16x16x32_bf16 v[150:153], v[114:117], v[162:165], v[150:153]
	v_mfma_f32_16x16x32_bf16 v[118:121], v[114:117], v[170:173], v[118:121]
	v_mfma_f32_16x16x32_bf16 v[126:129], v[98:101], v[170:173], v[126:129]
	v_mfma_f32_16x16x32_bf16 v[94:97], v[98:101], v[178:181], v[94:97]
	v_mfma_f32_16x16x32_bf16 v[90:93], v[114:117], v[178:181], v[90:93]
	v_mfma_f32_16x16x32_bf16 v[74:77], v[114:117], v[186:189], v[74:77]
	v_mfma_f32_16x16x32_bf16 v[78:81], v[98:101], v[186:189], v[78:81]
	v_mfma_f32_16x16x32_bf16 v[158:161], v[102:105], v[166:169], v[158:161]
	v_mfma_f32_16x16x32_bf16 v[150:153], v[122:125], v[166:169], v[150:153]
	v_mfma_f32_16x16x32_bf16 v[118:121], v[122:125], v[174:177], v[118:121]
	v_mfma_f32_16x16x32_bf16 v[126:129], v[102:105], v[174:177], v[126:129]
	v_mfma_f32_16x16x32_bf16 v[94:97], v[102:105], v[182:185], v[94:97]
	v_mfma_f32_16x16x32_bf16 v[90:93], v[122:125], v[182:185], v[90:93]
	v_mfma_f32_16x16x32_bf16 v[74:77], v[122:125], v[190:193], v[74:77]
	v_mfma_f32_16x16x32_bf16 v[78:81], v[102:105], v[190:193], v[78:81]
	s_setprio 0
	s_setprio 1
	v_mfma_f32_16x16x32_bf16 v[142:145], v[130:133], v[162:165], v[142:145]
	v_mfma_f32_16x16x32_bf16 v[134:137], v[146:149], v[162:165], v[134:137]
	v_mfma_f32_16x16x32_bf16 v[106:109], v[146:149], v[170:173], v[106:109]
	v_mfma_f32_16x16x32_bf16 v[110:113], v[130:133], v[170:173], v[110:113]
	v_mfma_f32_16x16x32_bf16 v[86:89], v[130:133], v[178:181], v[86:89]
	v_mfma_f32_16x16x32_bf16 v[82:85], v[146:149], v[178:181], v[82:85]
	v_mfma_f32_16x16x32_bf16 v[66:69], v[146:149], v[186:189], v[66:69]
	v_mfma_f32_16x16x32_bf16 v[70:73], v[130:133], v[186:189], v[70:73]
	v_mfma_f32_16x16x32_bf16 v[142:145], v[138:141], v[166:169], v[142:145]
	v_mfma_f32_16x16x32_bf16 v[134:137], v[154:157], v[166:169], v[134:137]
	v_mfma_f32_16x16x32_bf16 v[106:109], v[154:157], v[174:177], v[106:109]
	v_mfma_f32_16x16x32_bf16 v[110:113], v[138:141], v[174:177], v[110:113]
	v_mfma_f32_16x16x32_bf16 v[86:89], v[138:141], v[182:185], v[86:89]
	v_mfma_f32_16x16x32_bf16 v[82:85], v[154:157], v[182:185], v[82:85]
	v_mfma_f32_16x16x32_bf16 v[66:69], v[154:157], v[190:193], v[66:69]
	v_mfma_f32_16x16x32_bf16 v[70:73], v[138:141], v[190:193], v[70:73]
	s_setprio 0
	s_barrier
	s_add_i32 vcc_hi, vcc_hi, s80
	v_lshl_add_u64 v[206:207], s[4:5], 0, v[0:1]
	s_mov_b32 m0, vcc_hi
	ds_read_b128 v[162:165], v249 offset:16384
	ds_read_b128 v[166:169], v249 offset:17408
	ds_read_b128 v[170:173], v249 offset:18432
	ds_read_b128 v[174:177], v249 offset:19456
	ds_read_b128 v[178:181], v249 offset:20480
	ds_read_b128 v[182:185], v249 offset:21504
	ds_read_b128 v[186:189], v249 offset:22528
	ds_read_b128 v[190:193], v249 offset:23552
	global_load_lds_dwordx4 v[206:207], off
	s_add_i32 m0, vcc_hi, 0x2000
	v_lshl_add_u64 v[212:213], s[4:5], 0, v[198:199]
	s_add_u32 s4, s4, s58
	s_addc_u32 s5, s5, 0
	s_add_i32 s84, s84, s80
	global_load_lds_dwordx4 v[212:213], off
	v_lshl_add_u64 v[214:215], s[4:5], 0, v[0:1]
	s_mov_b32 m0, s84
	v_lshl_add_u64 v[216:217], s[4:5], 0, v[198:199]
	global_load_lds_dwordx4 v[214:215], off
	s_add_i32 m0, s84, 0x2000
	v_lshl_add_u64 v[218:219], s[8:9], 0, v[194:195]
	global_load_lds_dwordx4 v[216:217], off
	s_mov_b32 m0, s81
	v_lshl_add_u64 v[220:221], s[8:9], 0, v[196:197]
	global_load_lds_dwordx4 v[218:219], off
	s_mov_b32 m0, s70
	s_nop 0
	global_load_lds_dwordx4 v[220:221], off
	s_waitcnt vmcnt(8)
	s_waitcnt lgkmcnt(0)
	s_barrier
	s_setprio 1
	s_waitcnt lgkmcnt(0)
	v_mfma_f32_16x16x32_bf16 v[62:65], v[98:101], v[162:165], v[62:65]
	v_mfma_f32_16x16x32_bf16 v[58:61], v[114:117], v[162:165], v[58:61]
	v_mfma_f32_16x16x32_bf16 v[42:45], v[114:117], v[170:173], v[42:45]
	v_mfma_f32_16x16x32_bf16 v[46:49], v[98:101], v[170:173], v[46:49]
	v_mfma_f32_16x16x32_bf16 v[30:33], v[98:101], v[178:181], v[30:33]
	v_mfma_f32_16x16x32_bf16 v[26:29], v[114:117], v[178:181], v[26:29]
	v_mfma_f32_16x16x32_bf16 v[10:13], v[114:117], v[186:189], v[10:13]
	v_mfma_f32_16x16x32_bf16 v[14:17], v[98:101], v[186:189], v[14:17]
	v_mfma_f32_16x16x32_bf16 v[62:65], v[102:105], v[166:169], v[62:65]
	v_mfma_f32_16x16x32_bf16 v[58:61], v[122:125], v[166:169], v[58:61]
	v_mfma_f32_16x16x32_bf16 v[42:45], v[122:125], v[174:177], v[42:45]
	v_mfma_f32_16x16x32_bf16 v[46:49], v[102:105], v[174:177], v[46:49]
	v_mfma_f32_16x16x32_bf16 v[30:33], v[102:105], v[182:185], v[30:33]
	v_mfma_f32_16x16x32_bf16 v[26:29], v[122:125], v[182:185], v[26:29]
	v_mfma_f32_16x16x32_bf16 v[10:13], v[122:125], v[190:193], v[10:13]
	v_mfma_f32_16x16x32_bf16 v[14:17], v[102:105], v[190:193], v[14:17]
	s_setprio 0
	s_setprio 1
	v_mfma_f32_16x16x32_bf16 v[54:57], v[130:133], v[162:165], v[54:57]
	v_mfma_f32_16x16x32_bf16 v[50:53], v[146:149], v[162:165], v[50:53]
	v_mfma_f32_16x16x32_bf16 v[34:37], v[146:149], v[170:173], v[34:37]
	v_mfma_f32_16x16x32_bf16 v[38:41], v[130:133], v[170:173], v[38:41]
	v_mfma_f32_16x16x32_bf16 v[22:25], v[130:133], v[178:181], v[22:25]
	v_mfma_f32_16x16x32_bf16 v[18:21], v[146:149], v[178:181], v[18:21]
	v_mfma_f32_16x16x32_bf16 v[2:5], v[146:149], v[186:189], v[2:5]
	v_mfma_f32_16x16x32_bf16 v[6:9], v[130:133], v[186:189], v[6:9]
	v_mfma_f32_16x16x32_bf16 v[54:57], v[138:141], v[166:169], v[54:57]
	v_mfma_f32_16x16x32_bf16 v[50:53], v[154:157], v[166:169], v[50:53]
	v_mfma_f32_16x16x32_bf16 v[34:37], v[154:157], v[174:177], v[34:37]
	v_mfma_f32_16x16x32_bf16 v[38:41], v[138:141], v[174:177], v[38:41]
	v_mfma_f32_16x16x32_bf16 v[22:25], v[138:141], v[182:185], v[22:25]
	v_mfma_f32_16x16x32_bf16 v[18:21], v[154:157], v[182:185], v[18:21]
	v_mfma_f32_16x16x32_bf16 v[2:5], v[154:157], v[190:193], v[2:5]
	v_mfma_f32_16x16x32_bf16 v[6:9], v[138:141], v[190:193], v[6:9]
	s_setprio 0
	s_barrier
; #define PG8_STAGE(bufoff, gbase, voff) do { _Pragma("unroll") for (int _i = 0; _i < 2; ++_i) \
;         __builtin_amdgcn_global_load_lds((const unsigned*)((const char*)(gbase) + (voff)[_i]), (PG8_LAS unsigned*)(lds + (bufoff) + ldsw + _i * 8192), 16, 0, 0); } while (0)
; #define PG8_LDA(dst, b, h) do { _Pragma("unroll") for (int m = 0; m < 4; ++m) _Pragma("unroll") for (int k = 0; k < 2; ++k) dst[m][k] = *(const PG8_LAS bf16x8*)(lds + PG8_SA(b, h) + aoff + m * 2048 + k * 1024); } while (0)
; #define PG8_LDB(dst, b, h) do { _Pragma("unroll") for (int n = 0; n < 2; ++n) _Pragma("unroll") for (int k = 0; k < 2; ++k) dst[n][k] = *(const PG8_LAS bf16x8*)(lds + PG8_SB(b, h) + boff + n * 2048 + k * 1024); } while (0)
; #define PG8_MMA(ai, bj, At, Bt) do { __builtin_amdgcn_s_setprio(1); _Pragma("unroll") for (int m = 0; m < 4; ++m) _Pragma("unroll") for (int n = 0; n < 2; ++n) _Pragma("unroll") for (int k = 0; k < 2; ++k) \
;         acc[ai][bj][m][n] = mma16<Epi::I8>(Bt[n][k], At[m][k], acc[ai][bj][m][n]); __builtin_amdgcn_s_setprio(0); } while (0)
; #define PG8_WAIT_V(n) asm volatile("s_waitcnt vmcnt(" #n ")" ::: "memory")
; #define PG8_WAIT_L(n) asm volatile("s_waitcnt lgkmcnt(" #n ")" ::: "memory")
; #define PG8_BAR __builtin_amdgcn_s_barrier()
; #define PG8_SCHED __builtin_amdgcn_sched_barrier(0)
; template <class Epi, class Sched, bool ALIGN_EPI = false, bool SP2 = false>
; __device__ __forceinline__ void gemm_phase(PG8_LAS unsigned char* lds, const Gemm g, const Sched& S, const Epi& E) {
;     ...
;             PG8_LDB(B0, 1, 0); PG8_LDB(B1, 1, 1); PG8_SCHED; PG8_LDA(At, 1, 0); PG8_STAGE(PG8_SA(0, 1), a2 + hstep, voffA);
;             PG8_WAIT_V(8); PG8_WAIT_L(0); PG8_BAR; PG8_MMA(0, 0, At, B0); PG8_MMA(0, 1, At, B1); PG8_BAR; PG8_SCHED;
	s_add_i32 s84, 0, 0x18000
	s_add_i32 vcc_hi, 0, 0x1c000
	v_add_u32_e32 v122, s84, v248
	v_add_u32_e32 v154, vcc_hi, v248
	ds_read_b128 v[98:101], v122
	ds_read_b128 v[102:105], v122 offset:1024
	ds_read_b128 v[114:117], v122 offset:2048
	ds_read_b128 v[122:125], v122 offset:3072
	ds_read_b128 v[130:133], v154
	ds_read_b128 v[138:141], v154 offset:1024
	ds_read_b128 v[146:149], v154 offset:2048
	ds_read_b128 v[154:157], v154 offset:3072
	s_add_u32 s4, s8, s100
	s_addc_u32 s5, s9, 0
	s_mov_b32 m0, s71
	v_lshl_add_u64 v[222:223], s[4:5], 0, v[194:195]
	ds_read_b128 v[162:165], v249 offset:32768
	ds_read_b128 v[166:169], v249 offset:33792
	ds_read_b128 v[170:173], v249 offset:34816
	ds_read_b128 v[174:177], v249 offset:35840
	ds_read_b128 v[178:181], v249 offset:36864
	ds_read_b128 v[182:185], v249 offset:37888
	ds_read_b128 v[186:189], v249 offset:38912
	ds_read_b128 v[190:193], v249 offset:39936
	global_load_lds_dwordx4 v[222:223], off
	v_lshl_add_u64 v[222:223], s[4:5], 0, v[196:197]
	s_mov_b32 m0, s12
	s_nop 0
	global_load_lds_dwordx4 v[222:223], off
	s_waitcnt vmcnt(8)
	s_waitcnt lgkmcnt(0)
	s_barrier
	s_setprio 1
	s_waitcnt lgkmcnt(0)
	v_mfma_f32_16x16x32_bf16 v[158:161], v[98:101], v[162:165], v[158:161]
	v_mfma_f32_16x16x32_bf16 v[150:153], v[114:117], v[162:165], v[150:153]
	v_mfma_f32_16x16x32_bf16 v[118:121], v[114:117], v[170:173], v[118:121]
	v_mfma_f32_16x16x32_bf16 v[126:129], v[98:101], v[170:173], v[126:129]
	v_mfma_f32_16x16x32_bf16 v[94:97], v[98:101], v[178:181], v[94:97]
	v_mfma_f32_16x16x32_bf16 v[90:93], v[114:117], v[178:181], v[90:93]
	v_mfma_f32_16x16x32_bf16 v[74:77], v[114:117], v[186:189], v[74:77]
	v_mfma_f32_16x16x32_bf16 v[78:81], v[98:101], v[186:189], v[78:81]
	v_mfma_f32_16x16x32_bf16 v[158:161], v[102:105], v[166:169], v[158:161]
	v_mfma_f32_16x16x32_bf16 v[150:153], v[122:125], v[166:169], v[150:153]
	v_mfma_f32_16x16x32_bf16 v[118:121], v[122:125], v[174:177], v[118:121]
	v_mfma_f32_16x16x32_bf16 v[126:129], v[102:105], v[174:177], v[126:129]
	v_mfma_f32_16x16x32_bf16 v[94:97], v[102:105], v[182:185], v[94:97]
	v_mfma_f32_16x16x32_bf16 v[90:93], v[122:125], v[182:185], v[90:93]
	v_mfma_f32_16x16x32_bf16 v[74:77], v[122:125], v[190:193], v[74:77]
	v_mfma_f32_16x16x32_bf16 v[78:81], v[102:105], v[190:193], v[78:81]
	s_setprio 0
	s_setprio 1
	v_mfma_f32_16x16x32_bf16 v[142:145], v[130:133], v[162:165], v[142:145]
	v_mfma_f32_16x16x32_bf16 v[134:137], v[146:149], v[162:165], v[134:137]
	v_mfma_f32_16x16x32_bf16 v[106:109], v[146:149], v[170:173], v[106:109]
	v_mfma_f32_16x16x32_bf16 v[110:113], v[130:133], v[170:173], v[110:113]
	v_mfma_f32_16x16x32_bf16 v[86:89], v[130:133], v[178:181], v[86:89]
	v_mfma_f32_16x16x32_bf16 v[82:85], v[146:149], v[178:181], v[82:85]
	v_mfma_f32_16x16x32_bf16 v[66:69], v[146:149], v[186:189], v[66:69]
	v_mfma_f32_16x16x32_bf16 v[70:73], v[130:133], v[186:189], v[70:73]
	v_mfma_f32_16x16x32_bf16 v[142:145], v[138:141], v[166:169], v[142:145]
	v_mfma_f32_16x16x32_bf16 v[134:137], v[154:157], v[166:169], v[134:137]
	v_mfma_f32_16x16x32_bf16 v[106:109], v[154:157], v[174:177], v[106:109]
	v_mfma_f32_16x16x32_bf16 v[110:113], v[138:141], v[174:177], v[110:113]
	v_mfma_f32_16x16x32_bf16 v[86:89], v[138:141], v[182:185], v[86:89]
	v_mfma_f32_16x16x32_bf16 v[82:85], v[154:157], v[182:185], v[82:85]
	v_mfma_f32_16x16x32_bf16 v[66:69], v[154:157], v[190:193], v[66:69]
	v_mfma_f32_16x16x32_bf16 v[70:73], v[138:141], v[190:193], v[70:73]
	s_setprio 0
	s_barrier
; #define PG8_STAGE(bufoff, gbase, voff) do { _Pragma("unroll") for (int _i = 0; _i < 2; ++_i) \
;         __builtin_amdgcn_global_load_lds((const unsigned*)((const char*)(gbase) + (voff)[_i]), (PG8_LAS unsigned*)(lds + (bufoff) + ldsw + _i * 8192), 16, 0, 0); } while (0)
; #define PG8_LDA(dst, b, h) do { _Pragma("unroll") for (int m = 0; m < 4; ++m) _Pragma("unroll") for (int k = 0; k < 2; ++k) dst[m][k] = *(const PG8_LAS bf16x8*)(lds + PG8_SA(b, h) + aoff + m * 2048 + k * 1024); } while (0)
; #define PG8_MMA(ai, bj, At, Bt) do { __builtin_amdgcn_s_setprio(1); _Pragma("unroll") for (int m = 0; m < 4; ++m) _Pragma("unroll") for (int n = 0; n < 2; ++n) _Pragma("unroll") for (int k = 0; k < 2; ++k) \
;         acc[ai][bj][m][n] = mma16<Epi::I8>(Bt[n][k], At[m][k], acc[ai][bj][m][n]); __builtin_amdgcn_s_setprio(0); } while (0)
; #define PG8_WAIT_V(n) asm volatile("s_waitcnt vmcnt(" #n ")" ::: "memory")
; #define PG8_WAIT_L(n) asm volatile("s_waitcnt lgkmcnt(" #n ")" ::: "memory")
; #define PG8_BAR __builtin_amdgcn_s_barrier()
; #define PG8_SCHED __builtin_amdgcn_sched_barrier(0)
; template <class Epi, class Sched, bool ALIGN_EPI = false, bool SP2 = false>
; __device__ __forceinline__ void gemm_phase(PG8_LAS unsigned char* lds, const Gemm g, const Sched& S, const Epi& E) {
;     ...
;         for (int t = 0; t < nt; t += 2) {
;             const bool last = (t == nt - 2);
;             const char* a1 = cA + (size_t)(t + 1) * kstep;
;             const char* a2 = last ? nA : cA + (size_t)(t + 2) * kstep; const char* b2 = last ? nB : cB + (size_t)(t + 2) * kstep;
;     ...
;             PG8_LDA(At, 1, 1); PG8_STAGE(PG8_SB(1, 0), b3, voffB); PG8_STAGE(PG8_SB(1, 1), b3 + hstep, voffB); PG8_STAGE(PG8_SA(1, 0), a3, voffA);
;             PG8_WAIT_V(8); PG8_WAIT_L(0); PG8_BAR; PG8_MMA(1, 0, At, B0); PG8_MMA(1, 1, At, B1); PG8_BAR; PG8_SCHED;
	s_add_i32 s4, s84, s80
	v_lshl_add_u64 v[206:207], v[206:207], 0, s[92:93]
	s_mov_b32 m0, s4
	ds_read_b128 v[162:165], v249 offset:49152
	ds_read_b128 v[166:169], v249 offset:50176
	ds_read_b128 v[170:173], v249 offset:51200
	ds_read_b128 v[174:177], v249 offset:52224
	ds_read_b128 v[178:181], v249 offset:53248
	ds_read_b128 v[182:185], v249 offset:54272
	ds_read_b128 v[186:189], v249 offset:55296
	ds_read_b128 v[190:193], v249 offset:56320
	global_load_lds_dwordx4 v[206:207], off
	v_lshl_add_u64 v[206:207], v[212:213], 0, s[92:93]
	s_add_i32 m0, s4, 0x2000
	s_add_i32 s4, vcc_hi, s80
	global_load_lds_dwordx4 v[206:207], off
	v_lshl_add_u64 v[206:207], v[214:215], 0, s[92:93]
	s_mov_b32 m0, s4
	s_nop 0
	global_load_lds_dwordx4 v[206:207], off
	v_lshl_add_u64 v[206:207], v[216:217], 0, s[92:93]
	s_add_i32 m0, s4, 0x2000
	s_nop 0
	global_load_lds_dwordx4 v[206:207], off
	v_lshl_add_u64 v[206:207], v[218:219], 0, s[98:99]
	s_mov_b32 m0, s10
	s_nop 0
	global_load_lds_dwordx4 v[206:207], off
	v_lshl_add_u64 v[206:207], v[220:221], 0, s[98:99]
	s_mov_b32 m0, s11
	s_nop 0
	global_load_lds_dwordx4 v[206:207], off
	s_waitcnt vmcnt(8)
	s_waitcnt lgkmcnt(0)
	s_barrier
	s_setprio 1
	s_waitcnt lgkmcnt(0)
	v_mfma_f32_16x16x32_bf16 v[62:65], v[98:101], v[162:165], v[62:65]
	v_mfma_f32_16x16x32_bf16 v[58:61], v[114:117], v[162:165], v[58:61]
	v_mfma_f32_16x16x32_bf16 v[42:45], v[114:117], v[170:173], v[42:45]
	v_mfma_f32_16x16x32_bf16 v[46:49], v[98:101], v[170:173], v[46:49]
	v_mfma_f32_16x16x32_bf16 v[30:33], v[98:101], v[178:181], v[30:33]
	v_mfma_f32_16x16x32_bf16 v[26:29], v[114:117], v[178:181], v[26:29]
	v_mfma_f32_16x16x32_bf16 v[10:13], v[114:117], v[186:189], v[10:13]
	v_mfma_f32_16x16x32_bf16 v[14:17], v[98:101], v[186:189], v[14:17]
	v_mfma_f32_16x16x32_bf16 v[62:65], v[102:105], v[166:169], v[62:65]
	v_mfma_f32_16x16x32_bf16 v[58:61], v[122:125], v[166:169], v[58:61]
	v_mfma_f32_16x16x32_bf16 v[42:45], v[122:125], v[174:177], v[42:45]
	v_mfma_f32_16x16x32_bf16 v[46:49], v[102:105], v[174:177], v[46:49]
	v_mfma_f32_16x16x32_bf16 v[30:33], v[102:105], v[182:185], v[30:33]
	v_mfma_f32_16x16x32_bf16 v[26:29], v[122:125], v[182:185], v[26:29]
	v_mfma_f32_16x16x32_bf16 v[10:13], v[122:125], v[190:193], v[10:13]
	v_mfma_f32_16x16x32_bf16 v[14:17], v[102:105], v[190:193], v[14:17]
	s_setprio 0
	s_setprio 1
	v_mfma_f32_16x16x32_bf16 v[54:57], v[130:133], v[162:165], v[54:57]
	v_mfma_f32_16x16x32_bf16 v[50:53], v[146:149], v[162:165], v[50:53]
	v_mfma_f32_16x16x32_bf16 v[34:37], v[146:149], v[170:173], v[34:37]
	v_mfma_f32_16x16x32_bf16 v[38:41], v[130:133], v[170:173], v[38:41]
	v_mfma_f32_16x16x32_bf16 v[22:25], v[130:133], v[178:181], v[22:25]
	v_mfma_f32_16x16x32_bf16 v[18:21], v[146:149], v[178:181], v[18:21]
	v_mfma_f32_16x16x32_bf16 v[2:5], v[146:149], v[186:189], v[2:5]
	v_mfma_f32_16x16x32_bf16 v[6:9], v[130:133], v[186:189], v[6:9]
	v_mfma_f32_16x16x32_bf16 v[54:57], v[138:141], v[166:169], v[54:57]
	v_mfma_f32_16x16x32_bf16 v[50:53], v[154:157], v[166:169], v[50:53]
	v_mfma_f32_16x16x32_bf16 v[34:37], v[154:157], v[174:177], v[34:37]
	v_mfma_f32_16x16x32_bf16 v[38:41], v[138:141], v[174:177], v[38:41]
	v_mfma_f32_16x16x32_bf16 v[22:25], v[138:141], v[182:185], v[22:25]
	v_mfma_f32_16x16x32_bf16 v[18:21], v[154:157], v[182:185], v[18:21]
	v_mfma_f32_16x16x32_bf16 v[2:5], v[154:157], v[190:193], v[2:5]
	v_mfma_f32_16x16x32_bf16 v[6:9], v[138:141], v[190:193], v[6:9]
	s_setprio 0
	s_barrier
	s_add_u32 s6, s6, s98
	s_addc_u32 s7, s7, 0
	s_add_u32 s6, s6, s98
	s_addc_u32 s7, s7, 0
	s_add_u32 s67, s67, 0x100
	s_addc_u32 s85, s85, 0
	s_cmp_ge_u32 vcc_lo, s69
	s_mov_b32 s8, vcc_lo
	s_cbranch_scc0 .LBB0_175
